# hand-written layer-0 pooling prep (row-sum rstd batched 3 rows per wave, pipelined window trips) on top of the layer-1 prep and conversion/deferral edits
# speedup vs baseline: 1.0183x; 1.0006x over previous
.LBB0_908:
	s_or_b64 exec, exec, s[4:5]
	s_waitcnt lgkmcnt(0)
	s_mov_b64 s[22:23], s[78:79]
	v_mov_b32_e32 v0, v170
	s_barrier
	s_load_dwordx2 s[4:5], s[78:79], 0xa0
	s_load_dwordx2 s[6:7], s[78:79], 0x28
	s_load_dwordx2 s[8:9], s[78:79], 0x98
	s_load_dwordx2 s[10:11], s[78:79], 0x10
	s_load_dwordx4 s[12:15], s[78:79], 0x0
	v_and_b32_e32 v28, 63, v170
	v_lshrrev_b32_e32 v29, 6, v170
	v_lshlrev_b32_e32 v21, 4, v170
	v_lshlrev_b32_e32 v20, 2, v28
	v_readfirstlane_b32 s2, v29
	v_and_b32_e32 v22, 0x7f, v170
	v_lshlrev_b32_e32 v22, 3, v22
	v_lshlrev_b32_e32 v23, 4, v28
	s_lshr_b32 s0, s2, 1
	s_lshl_b32 s1, 2, s0
	s_mul_i32 s41, s0, 0x948000
	v_add_u32_e32 v22, s41, v22
	s_add_u32 s40, s0, 1
	s_lshl_b32 s40, s40, 23
	s_sub_u32 s40, 0x3f800000, s40
	v_mov_b32_e32 v27, s40
	s_lshr_b32 s44, s76, 6
	s_and_b32 s45, s76, 63
	s_cmp_eq_u32 s45, 0
	s_cselect_b32 s38, 1, 0
	s_cmp_eq_u32 s45, 63
	s_cselect_b32 s39, 1, 0
	s_lshl_b32 s45, s45, 5
	s_lshl_b32 s50, s44, 11
	s_add_u32 s50, s50, s45
	s_sub_i32 s52, s50, 15
	s_sub_u32 s53, 16, s1
	s_sub_u32 s37, s1, 1
	s_cmp_eq_u32 s38, 1
	s_cselect_b32 s36, 15, s53
	s_cselect_b32 s37, s37, 0
	s_cselect_b32 s62, 15, 0
	s_waitcnt lgkmcnt(0)
	s_mov_b64 s[16:17], s[12:13]
	s_add_u32 s18, s4, 0x1d900000
	s_addc_u32 s19, s5, 0
	global_load_dwordx4 v[2:5], v21, s[6:7]
	s_add_u32 s41, s2, 0
	s_max_u32 s41, s41, s62
	s_min_u32 s41, s41, 46
	s_lshl_b32 s24, s41, 2
	s_add_i32 s41, s41, s52
	s_lshl_b32 s12, s41, 13
	s_lshr_b32 s13, s41, 19
	s_add_u32 s20, s16, s12
	s_addc_u32 s21, s17, s13
	s_add_u32 s48, s20, 0x1000
	s_addc_u32 s49, s21, 0
	global_load_dwordx4 v[34:37], v23, s[20:21] offset:0
	global_load_dwordx4 v[38:41], v23, s[20:21] offset:1024
	global_load_dwordx4 v[42:45], v23, s[20:21] offset:2048
	global_load_dwordx4 v[46:49], v23, s[20:21] offset:3072
	global_load_dwordx4 v[50:53], v23, s[48:49] offset:0
	global_load_dwordx4 v[54:57], v23, s[48:49] offset:1024
	global_load_dwordx4 v[58:61], v23, s[48:49] offset:2048
	global_load_dwordx4 v[62:65], v23, s[48:49] offset:3072
	s_add_u32 s41, s2, 8
	s_max_u32 s41, s41, s62
	s_min_u32 s41, s41, 46
	s_lshl_b32 s25, s41, 2
	s_add_i32 s41, s41, s52
	s_lshl_b32 s12, s41, 13
	s_lshr_b32 s13, s41, 19
	s_add_u32 s20, s16, s12
	s_addc_u32 s21, s17, s13
	s_add_u32 s48, s20, 0x1000
	s_addc_u32 s49, s21, 0
	global_load_dwordx4 v[66:69], v23, s[20:21] offset:0
	global_load_dwordx4 v[70:73], v23, s[20:21] offset:1024
	global_load_dwordx4 v[74:77], v23, s[20:21] offset:2048
	global_load_dwordx4 v[78:81], v23, s[20:21] offset:3072
	global_load_dwordx4 v[82:85], v23, s[48:49] offset:0
	global_load_dwordx4 v[86:89], v23, s[48:49] offset:1024
	global_load_dwordx4 v[90:93], v23, s[48:49] offset:2048
	global_load_dwordx4 v[94:97], v23, s[48:49] offset:3072
	s_add_u32 s41, s2, 16
	s_max_u32 s41, s41, s62
	s_min_u32 s41, s41, 46
	s_lshl_b32 s26, s41, 2
	s_add_i32 s41, s41, s52
	s_lshl_b32 s12, s41, 13
	s_lshr_b32 s13, s41, 19
	s_add_u32 s20, s16, s12
	s_addc_u32 s21, s17, s13
	s_add_u32 s48, s20, 0x1000
	s_addc_u32 s49, s21, 0
	global_load_dwordx4 v[98:101], v23, s[20:21] offset:0
	global_load_dwordx4 v[102:105], v23, s[20:21] offset:1024
	global_load_dwordx4 v[106:109], v23, s[20:21] offset:2048
	global_load_dwordx4 v[110:113], v23, s[20:21] offset:3072
	global_load_dwordx4 v[114:117], v23, s[48:49] offset:0
	global_load_dwordx4 v[118:121], v23, s[48:49] offset:1024
	global_load_dwordx4 v[122:125], v23, s[48:49] offset:2048
	global_load_dwordx4 v[126:129], v23, s[48:49] offset:3072
	s_waitcnt vmcnt(0)
	v_mul_f32_e32 v130, v34, v34
	v_fmac_f32_e32 v130, v35, v35
	v_fmac_f32_e32 v130, v36, v36
	v_fmac_f32_e32 v130, v37, v37
	v_fmac_f32_e32 v130, v38, v38
	v_fmac_f32_e32 v130, v39, v39
	v_fmac_f32_e32 v130, v40, v40
	v_fmac_f32_e32 v130, v41, v41
	v_fmac_f32_e32 v130, v42, v42
	v_fmac_f32_e32 v130, v43, v43
	v_fmac_f32_e32 v130, v44, v44
	v_fmac_f32_e32 v130, v45, v45
	v_fmac_f32_e32 v130, v46, v46
	v_fmac_f32_e32 v130, v47, v47
	v_fmac_f32_e32 v130, v48, v48
	v_fmac_f32_e32 v130, v49, v49
	v_fmac_f32_e32 v130, v50, v50
	v_fmac_f32_e32 v130, v51, v51
	v_fmac_f32_e32 v130, v52, v52
	v_fmac_f32_e32 v130, v53, v53
	v_fmac_f32_e32 v130, v54, v54
	v_fmac_f32_e32 v130, v55, v55
	v_fmac_f32_e32 v130, v56, v56
	v_fmac_f32_e32 v130, v57, v57
	v_fmac_f32_e32 v130, v58, v58
	v_fmac_f32_e32 v130, v59, v59
	v_fmac_f32_e32 v130, v60, v60
	v_fmac_f32_e32 v130, v61, v61
	v_fmac_f32_e32 v130, v62, v62
	v_fmac_f32_e32 v130, v63, v63
	v_fmac_f32_e32 v130, v64, v64
	v_fmac_f32_e32 v130, v65, v65
	v_mul_f32_e32 v131, v66, v66
	v_fmac_f32_e32 v131, v67, v67
	v_fmac_f32_e32 v131, v68, v68
	v_fmac_f32_e32 v131, v69, v69
	v_fmac_f32_e32 v131, v70, v70
	v_fmac_f32_e32 v131, v71, v71
	v_fmac_f32_e32 v131, v72, v72
	v_fmac_f32_e32 v131, v73, v73
	v_fmac_f32_e32 v131, v74, v74
	v_fmac_f32_e32 v131, v75, v75
	v_fmac_f32_e32 v131, v76, v76
	v_fmac_f32_e32 v131, v77, v77
	v_fmac_f32_e32 v131, v78, v78
	v_fmac_f32_e32 v131, v79, v79
	v_fmac_f32_e32 v131, v80, v80
	v_fmac_f32_e32 v131, v81, v81
	v_fmac_f32_e32 v131, v82, v82
	v_fmac_f32_e32 v131, v83, v83
	v_fmac_f32_e32 v131, v84, v84
	v_fmac_f32_e32 v131, v85, v85
	v_fmac_f32_e32 v131, v86, v86
	v_fmac_f32_e32 v131, v87, v87
	v_fmac_f32_e32 v131, v88, v88
	v_fmac_f32_e32 v131, v89, v89
	v_fmac_f32_e32 v131, v90, v90
	v_fmac_f32_e32 v131, v91, v91
	v_fmac_f32_e32 v131, v92, v92
	v_fmac_f32_e32 v131, v93, v93
	v_fmac_f32_e32 v131, v94, v94
	v_fmac_f32_e32 v131, v95, v95
	v_fmac_f32_e32 v131, v96, v96
	v_fmac_f32_e32 v131, v97, v97
	v_mul_f32_e32 v132, v98, v98
	v_fmac_f32_e32 v132, v99, v99
	v_fmac_f32_e32 v132, v100, v100
	v_fmac_f32_e32 v132, v101, v101
	v_fmac_f32_e32 v132, v102, v102
	v_fmac_f32_e32 v132, v103, v103
	v_fmac_f32_e32 v132, v104, v104
	v_fmac_f32_e32 v132, v105, v105
	v_fmac_f32_e32 v132, v106, v106
	v_fmac_f32_e32 v132, v107, v107
	v_fmac_f32_e32 v132, v108, v108
	v_fmac_f32_e32 v132, v109, v109
	v_fmac_f32_e32 v132, v110, v110
	v_fmac_f32_e32 v132, v111, v111
	v_fmac_f32_e32 v132, v112, v112
	v_fmac_f32_e32 v132, v113, v113
	v_fmac_f32_e32 v132, v114, v114
	v_fmac_f32_e32 v132, v115, v115
	v_fmac_f32_e32 v132, v116, v116
	v_fmac_f32_e32 v132, v117, v117
	v_fmac_f32_e32 v132, v118, v118
	v_fmac_f32_e32 v132, v119, v119
	v_fmac_f32_e32 v132, v120, v120
	v_fmac_f32_e32 v132, v121, v121
	v_fmac_f32_e32 v132, v122, v122
	v_fmac_f32_e32 v132, v123, v123
	v_fmac_f32_e32 v132, v124, v124
	v_fmac_f32_e32 v132, v125, v125
	v_fmac_f32_e32 v132, v126, v126
	v_fmac_f32_e32 v132, v127, v127
	v_fmac_f32_e32 v132, v128, v128
	v_fmac_f32_e32 v132, v129, v129
	v_xor_b32_e32 v136, 4, v20
	ds_bpermute_b32 v133, v136, v130
	ds_bpermute_b32 v134, v136, v131
	ds_bpermute_b32 v135, v136, v132
	s_waitcnt lgkmcnt(0)
	v_add_f32_e32 v130, v130, v133
	v_add_f32_e32 v131, v131, v134
	v_add_f32_e32 v132, v132, v135
	v_xor_b32_e32 v136, 8, v20
	ds_bpermute_b32 v133, v136, v130
	ds_bpermute_b32 v134, v136, v131
	ds_bpermute_b32 v135, v136, v132
	s_waitcnt lgkmcnt(0)
	v_add_f32_e32 v130, v130, v133
	v_add_f32_e32 v131, v131, v134
	v_add_f32_e32 v132, v132, v135
	v_xor_b32_e32 v136, 16, v20
	ds_bpermute_b32 v133, v136, v130
	ds_bpermute_b32 v134, v136, v131
	ds_bpermute_b32 v135, v136, v132
	s_waitcnt lgkmcnt(0)
	v_add_f32_e32 v130, v130, v133
	v_add_f32_e32 v131, v131, v134
	v_add_f32_e32 v132, v132, v135
	v_xor_b32_e32 v136, 32, v20
	ds_bpermute_b32 v133, v136, v130
	ds_bpermute_b32 v134, v136, v131
	ds_bpermute_b32 v135, v136, v132
	s_waitcnt lgkmcnt(0)
	v_add_f32_e32 v130, v130, v133
	v_add_f32_e32 v131, v131, v134
	v_add_f32_e32 v132, v132, v135
	v_xor_b32_e32 v136, 64, v20
	ds_bpermute_b32 v133, v136, v130
	ds_bpermute_b32 v134, v136, v131
	ds_bpermute_b32 v135, v136, v132
	s_waitcnt lgkmcnt(0)
	v_add_f32_e32 v130, v130, v133
	v_add_f32_e32 v131, v131, v134
	v_add_f32_e32 v132, v132, v135
	v_xor_b32_e32 v136, 128, v20
	ds_bpermute_b32 v133, v136, v130
	ds_bpermute_b32 v134, v136, v131
	ds_bpermute_b32 v135, v136, v132
	s_waitcnt lgkmcnt(0)
	v_add_f32_e32 v130, v130, v133
	v_add_f32_e32 v131, v131, v134
	v_add_f32_e32 v132, v132, v135
	v_mov_b32_e32 v30, v130
	v_fmamk_f32 v30, v30, 0x3a000000, v171
	v_mul_f32_e32 v28, 0x4f800000, v30
	v_cmp_gt_f32_e32 vcc, s51, v30
	s_nop 1
	v_cndmask_b32_e32 v30, v30, v28, vcc
	v_sqrt_f32_e32 v28, v30
	s_nop 0
	v_add_u32_e32 v29, -1, v28
	v_add_u32_e32 v31, 1, v28
	v_fma_f32 v32, -v29, v28, v30
	v_fma_f32 v33, -v31, v28, v30
	v_cmp_ge_f32_e64 s[34:35], 0, v32
	s_nop 1
	v_cndmask_b32_e64 v28, v28, v29, s[34:35]
	v_cmp_lt_f32_e64 s[34:35], 0, v33
	s_nop 1
	v_cndmask_b32_e64 v28, v28, v31, s[34:35]
	v_mul_f32_e32 v29, 0x37800000, v28
	v_cndmask_b32_e32 v28, v28, v29, vcc
	v_cmp_class_f32_e32 vcc, v30, v172
	s_nop 1
	v_cndmask_b32_e32 v30, v28, v30, vcc
	v_div_scale_f32 v28, s[34:35], v30, v30, 1.0
	v_rcp_f32_e32 v29, v28
	v_div_scale_f32 v31, vcc, 1.0, v30, 1.0
	v_fma_f32 v32, -v28, v29, 1.0
	v_fmac_f32_e32 v29, v32, v29
	v_mul_f32_e32 v32, v31, v29
	v_fma_f32 v33, -v28, v32, v31
	v_fmac_f32_e32 v32, v33, v29
	v_fma_f32 v28, -v28, v32, v31
	v_div_fmas_f32 v28, v28, v29, v32
	v_div_fixup_f32 v30, v28, v30, 1.0
	v_mov_b32_e32 v24, s24
	ds_write_b32 v24, v30
	v_mov_b32_e32 v30, v131
	v_fmamk_f32 v30, v30, 0x3a000000, v171
	v_mul_f32_e32 v28, 0x4f800000, v30
	v_cmp_gt_f32_e32 vcc, s51, v30
	s_nop 1
	v_cndmask_b32_e32 v30, v30, v28, vcc
	v_sqrt_f32_e32 v28, v30
	s_nop 0
	v_add_u32_e32 v29, -1, v28
	v_add_u32_e32 v31, 1, v28
	v_fma_f32 v32, -v29, v28, v30
	v_fma_f32 v33, -v31, v28, v30
	v_cmp_ge_f32_e64 s[34:35], 0, v32
	s_nop 1
	v_cndmask_b32_e64 v28, v28, v29, s[34:35]
	v_cmp_lt_f32_e64 s[34:35], 0, v33
	s_nop 1
	v_cndmask_b32_e64 v28, v28, v31, s[34:35]
	v_mul_f32_e32 v29, 0x37800000, v28
	v_cndmask_b32_e32 v28, v28, v29, vcc
	v_cmp_class_f32_e32 vcc, v30, v172
	s_nop 1
	v_cndmask_b32_e32 v30, v28, v30, vcc
	v_div_scale_f32 v28, s[34:35], v30, v30, 1.0
	v_rcp_f32_e32 v29, v28
	v_div_scale_f32 v31, vcc, 1.0, v30, 1.0
	v_fma_f32 v32, -v28, v29, 1.0
	v_fmac_f32_e32 v29, v32, v29
	v_mul_f32_e32 v32, v31, v29
	v_fma_f32 v33, -v28, v32, v31
	v_fmac_f32_e32 v32, v33, v29
	v_fma_f32 v28, -v28, v32, v31
	v_div_fmas_f32 v28, v28, v29, v32
	v_div_fixup_f32 v30, v28, v30, 1.0
	v_mov_b32_e32 v24, s25
	ds_write_b32 v24, v30
	v_mov_b32_e32 v30, v132
	v_fmamk_f32 v30, v30, 0x3a000000, v171
	v_mul_f32_e32 v28, 0x4f800000, v30
	v_cmp_gt_f32_e32 vcc, s51, v30
	s_nop 1
	v_cndmask_b32_e32 v30, v30, v28, vcc
	v_sqrt_f32_e32 v28, v30
	s_nop 0
	v_add_u32_e32 v29, -1, v28
	v_add_u32_e32 v31, 1, v28
	v_fma_f32 v32, -v29, v28, v30
	v_fma_f32 v33, -v31, v28, v30
	v_cmp_ge_f32_e64 s[34:35], 0, v32
	s_nop 1
	v_cndmask_b32_e64 v28, v28, v29, s[34:35]
	v_cmp_lt_f32_e64 s[34:35], 0, v33
	s_nop 1
	v_cndmask_b32_e64 v28, v28, v31, s[34:35]
	v_mul_f32_e32 v29, 0x37800000, v28
	v_cndmask_b32_e32 v28, v28, v29, vcc
	v_cmp_class_f32_e32 vcc, v30, v172
	s_nop 1
	v_cndmask_b32_e32 v30, v28, v30, vcc
	v_div_scale_f32 v28, s[34:35], v30, v30, 1.0
	v_rcp_f32_e32 v29, v28
	v_div_scale_f32 v31, vcc, 1.0, v30, 1.0
	v_fma_f32 v32, -v28, v29, 1.0
	v_fmac_f32_e32 v29, v32, v29
	v_mul_f32_e32 v32, v31, v29
	v_fma_f32 v33, -v28, v32, v31
	v_fmac_f32_e32 v32, v33, v29
	v_fma_f32 v28, -v28, v32, v31
	v_div_fmas_f32 v28, v28, v29, v32
	v_div_fixup_f32 v30, v28, v30, 1.0
	v_mov_b32_e32 v24, s26
	ds_write_b32 v24, v30
	s_add_u32 s41, s2, 24
	s_max_u32 s41, s41, s62
	s_min_u32 s41, s41, 46
	s_lshl_b32 s24, s41, 2
	s_add_i32 s41, s41, s52
	s_lshl_b32 s12, s41, 13
	s_lshr_b32 s13, s41, 19
	s_add_u32 s20, s16, s12
	s_addc_u32 s21, s17, s13
	s_add_u32 s48, s20, 0x1000
	s_addc_u32 s49, s21, 0
	global_load_dwordx4 v[34:37], v23, s[20:21] offset:0
	global_load_dwordx4 v[38:41], v23, s[20:21] offset:1024
	global_load_dwordx4 v[42:45], v23, s[20:21] offset:2048
	global_load_dwordx4 v[46:49], v23, s[20:21] offset:3072
	global_load_dwordx4 v[50:53], v23, s[48:49] offset:0
	global_load_dwordx4 v[54:57], v23, s[48:49] offset:1024
	global_load_dwordx4 v[58:61], v23, s[48:49] offset:2048
	global_load_dwordx4 v[62:65], v23, s[48:49] offset:3072
	s_add_u32 s41, s2, 32
	s_max_u32 s41, s41, s62
	s_min_u32 s41, s41, 46
	s_lshl_b32 s25, s41, 2
	s_add_i32 s41, s41, s52
	s_lshl_b32 s12, s41, 13
	s_lshr_b32 s13, s41, 19
	s_add_u32 s20, s16, s12
	s_addc_u32 s21, s17, s13
	s_add_u32 s48, s20, 0x1000
	s_addc_u32 s49, s21, 0
	global_load_dwordx4 v[66:69], v23, s[20:21] offset:0
	global_load_dwordx4 v[70:73], v23, s[20:21] offset:1024
	global_load_dwordx4 v[74:77], v23, s[20:21] offset:2048
	global_load_dwordx4 v[78:81], v23, s[20:21] offset:3072
	global_load_dwordx4 v[82:85], v23, s[48:49] offset:0
	global_load_dwordx4 v[86:89], v23, s[48:49] offset:1024
	global_load_dwordx4 v[90:93], v23, s[48:49] offset:2048
	global_load_dwordx4 v[94:97], v23, s[48:49] offset:3072
	s_add_u32 s41, s2, 40
	s_max_u32 s41, s41, s62
	s_min_u32 s41, s41, 46
	s_lshl_b32 s26, s41, 2
	s_add_i32 s41, s41, s52
	s_lshl_b32 s12, s41, 13
	s_lshr_b32 s13, s41, 19
	s_add_u32 s20, s16, s12
	s_addc_u32 s21, s17, s13
	s_add_u32 s48, s20, 0x1000
	s_addc_u32 s49, s21, 0
	global_load_dwordx4 v[98:101], v23, s[20:21] offset:0
	global_load_dwordx4 v[102:105], v23, s[20:21] offset:1024
	global_load_dwordx4 v[106:109], v23, s[20:21] offset:2048
	global_load_dwordx4 v[110:113], v23, s[20:21] offset:3072
	global_load_dwordx4 v[114:117], v23, s[48:49] offset:0
	global_load_dwordx4 v[118:121], v23, s[48:49] offset:1024
	global_load_dwordx4 v[122:125], v23, s[48:49] offset:2048
	global_load_dwordx4 v[126:129], v23, s[48:49] offset:3072
	s_waitcnt vmcnt(0)
	v_mul_f32_e32 v130, v34, v34
	v_fmac_f32_e32 v130, v35, v35
	v_fmac_f32_e32 v130, v36, v36
	v_fmac_f32_e32 v130, v37, v37
	v_fmac_f32_e32 v130, v38, v38
	v_fmac_f32_e32 v130, v39, v39
	v_fmac_f32_e32 v130, v40, v40
	v_fmac_f32_e32 v130, v41, v41
	v_fmac_f32_e32 v130, v42, v42
	v_fmac_f32_e32 v130, v43, v43
	v_fmac_f32_e32 v130, v44, v44
	v_fmac_f32_e32 v130, v45, v45
	v_fmac_f32_e32 v130, v46, v46
	v_fmac_f32_e32 v130, v47, v47
	v_fmac_f32_e32 v130, v48, v48
	v_fmac_f32_e32 v130, v49, v49
	v_fmac_f32_e32 v130, v50, v50
	v_fmac_f32_e32 v130, v51, v51
	v_fmac_f32_e32 v130, v52, v52
	v_fmac_f32_e32 v130, v53, v53
	v_fmac_f32_e32 v130, v54, v54
	v_fmac_f32_e32 v130, v55, v55
	v_fmac_f32_e32 v130, v56, v56
	v_fmac_f32_e32 v130, v57, v57
	v_fmac_f32_e32 v130, v58, v58
	v_fmac_f32_e32 v130, v59, v59
	v_fmac_f32_e32 v130, v60, v60
	v_fmac_f32_e32 v130, v61, v61
	v_fmac_f32_e32 v130, v62, v62
	v_fmac_f32_e32 v130, v63, v63
	v_fmac_f32_e32 v130, v64, v64
	v_fmac_f32_e32 v130, v65, v65
	v_mul_f32_e32 v131, v66, v66
	v_fmac_f32_e32 v131, v67, v67
	v_fmac_f32_e32 v131, v68, v68
	v_fmac_f32_e32 v131, v69, v69
	v_fmac_f32_e32 v131, v70, v70
	v_fmac_f32_e32 v131, v71, v71
	v_fmac_f32_e32 v131, v72, v72
	v_fmac_f32_e32 v131, v73, v73
	v_fmac_f32_e32 v131, v74, v74
	v_fmac_f32_e32 v131, v75, v75
	v_fmac_f32_e32 v131, v76, v76
	v_fmac_f32_e32 v131, v77, v77
	v_fmac_f32_e32 v131, v78, v78
	v_fmac_f32_e32 v131, v79, v79
	v_fmac_f32_e32 v131, v80, v80
	v_fmac_f32_e32 v131, v81, v81
	v_fmac_f32_e32 v131, v82, v82
	v_fmac_f32_e32 v131, v83, v83
	v_fmac_f32_e32 v131, v84, v84
	v_fmac_f32_e32 v131, v85, v85
	v_fmac_f32_e32 v131, v86, v86
	v_fmac_f32_e32 v131, v87, v87
	v_fmac_f32_e32 v131, v88, v88
	v_fmac_f32_e32 v131, v89, v89
	v_fmac_f32_e32 v131, v90, v90
	v_fmac_f32_e32 v131, v91, v91
	v_fmac_f32_e32 v131, v92, v92
	v_fmac_f32_e32 v131, v93, v93
	v_fmac_f32_e32 v131, v94, v94
	v_fmac_f32_e32 v131, v95, v95
	v_fmac_f32_e32 v131, v96, v96
	v_fmac_f32_e32 v131, v97, v97
	v_mul_f32_e32 v132, v98, v98
	v_fmac_f32_e32 v132, v99, v99
	v_fmac_f32_e32 v132, v100, v100
	v_fmac_f32_e32 v132, v101, v101
	v_fmac_f32_e32 v132, v102, v102
	v_fmac_f32_e32 v132, v103, v103
	v_fmac_f32_e32 v132, v104, v104
	v_fmac_f32_e32 v132, v105, v105
	v_fmac_f32_e32 v132, v106, v106
	v_fmac_f32_e32 v132, v107, v107
	v_fmac_f32_e32 v132, v108, v108
	v_fmac_f32_e32 v132, v109, v109
	v_fmac_f32_e32 v132, v110, v110
	v_fmac_f32_e32 v132, v111, v111
	v_fmac_f32_e32 v132, v112, v112
	v_fmac_f32_e32 v132, v113, v113
	v_fmac_f32_e32 v132, v114, v114
	v_fmac_f32_e32 v132, v115, v115
	v_fmac_f32_e32 v132, v116, v116
	v_fmac_f32_e32 v132, v117, v117
	v_fmac_f32_e32 v132, v118, v118
	v_fmac_f32_e32 v132, v119, v119
	v_fmac_f32_e32 v132, v120, v120
	v_fmac_f32_e32 v132, v121, v121
	v_fmac_f32_e32 v132, v122, v122
	v_fmac_f32_e32 v132, v123, v123
	v_fmac_f32_e32 v132, v124, v124
	v_fmac_f32_e32 v132, v125, v125
	v_fmac_f32_e32 v132, v126, v126
	v_fmac_f32_e32 v132, v127, v127
	v_fmac_f32_e32 v132, v128, v128
	v_fmac_f32_e32 v132, v129, v129
	v_xor_b32_e32 v136, 4, v20
	ds_bpermute_b32 v133, v136, v130
	ds_bpermute_b32 v134, v136, v131
	ds_bpermute_b32 v135, v136, v132
	s_waitcnt lgkmcnt(0)
	v_add_f32_e32 v130, v130, v133
	v_add_f32_e32 v131, v131, v134
	v_add_f32_e32 v132, v132, v135
	v_xor_b32_e32 v136, 8, v20
	ds_bpermute_b32 v133, v136, v130
	ds_bpermute_b32 v134, v136, v131
	ds_bpermute_b32 v135, v136, v132
	s_waitcnt lgkmcnt(0)
	v_add_f32_e32 v130, v130, v133
	v_add_f32_e32 v131, v131, v134
	v_add_f32_e32 v132, v132, v135
	v_xor_b32_e32 v136, 16, v20
	ds_bpermute_b32 v133, v136, v130
	ds_bpermute_b32 v134, v136, v131
	ds_bpermute_b32 v135, v136, v132
	s_waitcnt lgkmcnt(0)
	v_add_f32_e32 v130, v130, v133
	v_add_f32_e32 v131, v131, v134
	v_add_f32_e32 v132, v132, v135
	v_xor_b32_e32 v136, 32, v20
	ds_bpermute_b32 v133, v136, v130
	ds_bpermute_b32 v134, v136, v131
	ds_bpermute_b32 v135, v136, v132
	s_waitcnt lgkmcnt(0)
	v_add_f32_e32 v130, v130, v133
	v_add_f32_e32 v131, v131, v134
	v_add_f32_e32 v132, v132, v135
	v_xor_b32_e32 v136, 64, v20
	ds_bpermute_b32 v133, v136, v130
	ds_bpermute_b32 v134, v136, v131
	ds_bpermute_b32 v135, v136, v132
	s_waitcnt lgkmcnt(0)
	v_add_f32_e32 v130, v130, v133
	v_add_f32_e32 v131, v131, v134
	v_add_f32_e32 v132, v132, v135
	v_xor_b32_e32 v136, 128, v20
	ds_bpermute_b32 v133, v136, v130
	ds_bpermute_b32 v134, v136, v131
	ds_bpermute_b32 v135, v136, v132
	s_waitcnt lgkmcnt(0)
	v_add_f32_e32 v130, v130, v133
	v_add_f32_e32 v131, v131, v134
	v_add_f32_e32 v132, v132, v135
	v_mov_b32_e32 v30, v130
	v_fmamk_f32 v30, v30, 0x3a000000, v171
	v_mul_f32_e32 v28, 0x4f800000, v30
	v_cmp_gt_f32_e32 vcc, s51, v30
	s_nop 1
	v_cndmask_b32_e32 v30, v30, v28, vcc
	v_sqrt_f32_e32 v28, v30
	s_nop 0
	v_add_u32_e32 v29, -1, v28
	v_add_u32_e32 v31, 1, v28
	v_fma_f32 v32, -v29, v28, v30
	v_fma_f32 v33, -v31, v28, v30
	v_cmp_ge_f32_e64 s[34:35], 0, v32
	s_nop 1
	v_cndmask_b32_e64 v28, v28, v29, s[34:35]
	v_cmp_lt_f32_e64 s[34:35], 0, v33
	s_nop 1
	v_cndmask_b32_e64 v28, v28, v31, s[34:35]
	v_mul_f32_e32 v29, 0x37800000, v28
	v_cndmask_b32_e32 v28, v28, v29, vcc
	v_cmp_class_f32_e32 vcc, v30, v172
	s_nop 1
	v_cndmask_b32_e32 v30, v28, v30, vcc
	v_div_scale_f32 v28, s[34:35], v30, v30, 1.0
	v_rcp_f32_e32 v29, v28
	v_div_scale_f32 v31, vcc, 1.0, v30, 1.0
	v_fma_f32 v32, -v28, v29, 1.0
	v_fmac_f32_e32 v29, v32, v29
	v_mul_f32_e32 v32, v31, v29
	v_fma_f32 v33, -v28, v32, v31
	v_fmac_f32_e32 v32, v33, v29
	v_fma_f32 v28, -v28, v32, v31
	v_div_fmas_f32 v28, v28, v29, v32
	v_div_fixup_f32 v30, v28, v30, 1.0
	v_mov_b32_e32 v24, s24
	ds_write_b32 v24, v30
	v_mov_b32_e32 v30, v131
	v_fmamk_f32 v30, v30, 0x3a000000, v171
	v_mul_f32_e32 v28, 0x4f800000, v30
	v_cmp_gt_f32_e32 vcc, s51, v30
	s_nop 1
	v_cndmask_b32_e32 v30, v30, v28, vcc
	v_sqrt_f32_e32 v28, v30
	s_nop 0
	v_add_u32_e32 v29, -1, v28
	v_add_u32_e32 v31, 1, v28
	v_fma_f32 v32, -v29, v28, v30
	v_fma_f32 v33, -v31, v28, v30
	v_cmp_ge_f32_e64 s[34:35], 0, v32
	s_nop 1
	v_cndmask_b32_e64 v28, v28, v29, s[34:35]
	v_cmp_lt_f32_e64 s[34:35], 0, v33
	s_nop 1
	v_cndmask_b32_e64 v28, v28, v31, s[34:35]
	v_mul_f32_e32 v29, 0x37800000, v28
	v_cndmask_b32_e32 v28, v28, v29, vcc
	v_cmp_class_f32_e32 vcc, v30, v172
	s_nop 1
	v_cndmask_b32_e32 v30, v28, v30, vcc
	v_div_scale_f32 v28, s[34:35], v30, v30, 1.0
	v_rcp_f32_e32 v29, v28
	v_div_scale_f32 v31, vcc, 1.0, v30, 1.0
	v_fma_f32 v32, -v28, v29, 1.0
	v_fmac_f32_e32 v29, v32, v29
	v_mul_f32_e32 v32, v31, v29
	v_fma_f32 v33, -v28, v32, v31
	v_fmac_f32_e32 v32, v33, v29
	v_fma_f32 v28, -v28, v32, v31
	v_div_fmas_f32 v28, v28, v29, v32
	v_div_fixup_f32 v30, v28, v30, 1.0
	v_mov_b32_e32 v24, s25
	ds_write_b32 v24, v30
	v_mov_b32_e32 v30, v132
	v_fmamk_f32 v30, v30, 0x3a000000, v171
	v_mul_f32_e32 v28, 0x4f800000, v30
	v_cmp_gt_f32_e32 vcc, s51, v30
	s_nop 1
	v_cndmask_b32_e32 v30, v30, v28, vcc
	v_sqrt_f32_e32 v28, v30
	s_nop 0
	v_add_u32_e32 v29, -1, v28
	v_add_u32_e32 v31, 1, v28
	v_fma_f32 v32, -v29, v28, v30
	v_fma_f32 v33, -v31, v28, v30
	v_cmp_ge_f32_e64 s[34:35], 0, v32
	s_nop 1
	v_cndmask_b32_e64 v28, v28, v29, s[34:35]
	v_cmp_lt_f32_e64 s[34:35], 0, v33
	s_nop 1
	v_cndmask_b32_e64 v28, v28, v31, s[34:35]
	v_mul_f32_e32 v29, 0x37800000, v28
	v_cndmask_b32_e32 v28, v28, v29, vcc
	v_cmp_class_f32_e32 vcc, v30, v172
	s_nop 1
	v_cndmask_b32_e32 v30, v28, v30, vcc
	v_div_scale_f32 v28, s[34:35], v30, v30, 1.0
	v_rcp_f32_e32 v29, v28
	v_div_scale_f32 v31, vcc, 1.0, v30, 1.0
	v_fma_f32 v32, -v28, v29, 1.0
	v_fmac_f32_e32 v29, v32, v29
	v_mul_f32_e32 v32, v31, v29
	v_fma_f32 v33, -v28, v32, v31
	v_fmac_f32_e32 v32, v33, v29
	v_fma_f32 v28, -v28, v32, v31
	v_div_fmas_f32 v28, v28, v29, v32
	v_div_fixup_f32 v30, v28, v30, 1.0
	v_mov_b32_e32 v24, s26
	ds_write_b32 v24, v30
	s_waitcnt lgkmcnt(0)
	s_barrier
	s_lshl_b32 s12, s52, 13
	s_ashr_i32 s13, s52, 19
	s_add_u32 s48, s16, s12
	s_addc_u32 s49, s17, s13
	s_add_u32 s24, s48, 0x1e000
	s_addc_u32 s25, s49, 0
	s_lshl_b32 s12, s53, 13
	s_add_u32 s26, s48, s12
	s_addc_u32 s27, s49, 0
	s_mul_i32 s12, s50, 0x480
	s_add_u32 s28, s18, s12
	s_addc_u32 s29, s19, 0
	s_mul_i32 s12, s44, 0x1e000
	s_add_u32 s12, s12, 0x4200000
	s_add_u32 s30, s8, s12
	s_addc_u32 s31, s9, 0
	v_mov_b32_e32 v25, 0
	s_lshl_b32 s12, s53, 2
	v_mov_b32_e32 v26, s12
	s_cmp_eq_u32 s38, 1
	s_cbranch_scc1 .Lq0_noI
	global_load_dwordx4 v[34:37], v21, s[48:49]
	s_add_u32 s48, s48, 0x2000
	s_addc_u32 s49, s49, 0
	global_load_dwordx4 v[38:41], v21, s[48:49]
	s_add_u32 s48, s48, 0x2000
	s_addc_u32 s49, s49, 0
	global_load_dwordx4 v[42:45], v21, s[48:49]
	s_add_u32 s48, s48, 0x2000
	s_addc_u32 s49, s49, 0
	global_load_dwordx4 v[46:49], v21, s[48:49]
	s_add_u32 s48, s48, 0x2000
	s_addc_u32 s49, s49, 0
	global_load_dwordx4 v[50:53], v21, s[48:49]
	s_add_u32 s48, s48, 0x2000
	s_addc_u32 s49, s49, 0
	global_load_dwordx4 v[54:57], v21, s[48:49]
	s_add_u32 s48, s48, 0x2000
	s_addc_u32 s49, s49, 0
	global_load_dwordx4 v[58:61], v21, s[48:49]
	s_add_u32 s48, s48, 0x2000
	s_addc_u32 s49, s49, 0
	global_load_dwordx4 v[62:65], v21, s[48:49]
	s_add_u32 s48, s48, 0x2000
	s_addc_u32 s49, s49, 0
	global_load_dwordx4 v[66:69], v21, s[48:49]
	s_add_u32 s48, s48, 0x2000
	s_addc_u32 s49, s49, 0
	global_load_dwordx4 v[70:73], v21, s[48:49]
	s_add_u32 s48, s48, 0x2000
	s_addc_u32 s49, s49, 0
	global_load_dwordx4 v[74:77], v21, s[48:49]
	s_add_u32 s48, s48, 0x2000
	s_addc_u32 s49, s49, 0
	global_load_dwordx4 v[78:81], v21, s[48:49]
	s_add_u32 s48, s48, 0x2000
	s_addc_u32 s49, s49, 0
	global_load_dwordx4 v[82:85], v21, s[48:49]
	s_add_u32 s48, s48, 0x2000
	s_addc_u32 s49, s49, 0
	global_load_dwordx4 v[86:89], v21, s[48:49]
	s_add_u32 s48, s48, 0x2000
	s_addc_u32 s49, s49, 0
	global_load_dwordx4 v[90:93], v21, s[48:49]
	s_add_u32 s48, s48, 0x2000
	s_addc_u32 s49, s49, 0
.Lq0_noI:
	global_load_dwordx4 v[94:97], v21, s[24:25]
	s_add_u32 s24, s24, 0x2000
	s_addc_u32 s25, s25, 0
	global_load_dwordx4 v[98:101], v21, s[24:25]
	s_add_u32 s24, s24, 0x2000
	s_addc_u32 s25, s25, 0
	global_load_dwordx4 v[102:105], v21, s[24:25]
	s_add_u32 s24, s24, 0x2000
	s_addc_u32 s25, s25, 0
	global_load_dwordx4 v[106:109], v21, s[24:25]
	s_add_u32 s24, s24, 0x2000
	s_addc_u32 s25, s25, 0
	s_cmp_gt_u32 s37, 0
	s_cselect_b64 s[20:21], s[16:17], s[26:27]
	global_load_dwordx4 v[110:113], v21, s[20:21]
	s_add_u32 s26, s26, 0x2000
	s_addc_u32 s27, s27, 0
	s_cmp_gt_u32 s37, 1
	s_cselect_b64 s[20:21], s[16:17], s[26:27]
	global_load_dwordx4 v[114:117], v21, s[20:21]
	s_add_u32 s26, s26, 0x2000
	s_addc_u32 s27, s27, 0
	s_cmp_gt_u32 s37, 2
	s_cselect_b64 s[20:21], s[16:17], s[26:27]
	global_load_dwordx4 v[118:121], v21, s[20:21]
	s_add_u32 s26, s26, 0x2000
	s_addc_u32 s27, s27, 0
	s_cmp_gt_u32 s37, 3
	s_cselect_b64 s[20:21], s[16:17], s[26:27]
	global_load_dwordx4 v[122:125], v21, s[20:21]
	s_add_u32 s26, s26, 0x2000
	s_addc_u32 s27, s27, 0
	ds_read_b32 v126, v25 offset:0
	ds_read_b32 v127, v25 offset:4
	ds_read_b32 v128, v25 offset:8
	ds_read_b32 v129, v25 offset:12
	ds_read_b32 v130, v25 offset:16
	ds_read_b32 v131, v25 offset:20
	ds_read_b32 v132, v25 offset:24
	ds_read_b32 v133, v25 offset:28
	ds_read_b32 v134, v25 offset:32
	ds_read_b32 v135, v25 offset:36
	ds_read_b32 v136, v25 offset:40
	ds_read_b32 v137, v25 offset:44
	ds_read_b32 v138, v25 offset:48
	ds_read_b32 v139, v25 offset:52
	ds_read_b32 v142, v25 offset:56
	ds_read_b32 v144, v25 offset:60
	ds_read_b32 v145, v25 offset:64
	ds_read_b32 v146, v25 offset:68
	ds_read_b32 v147, v25 offset:72
	ds_read_b32 v148, v26 offset:0
	ds_read_b32 v149, v26 offset:4
	ds_read_b32 v150, v26 offset:8
	ds_read_b32 v151, v26 offset:12
	v_mov_b32_e32 v6, 0
	v_mov_b32_e32 v7, 0
	v_mov_b32_e32 v8, 0
	v_mov_b32_e32 v9, 0
	s_waitcnt vmcnt(0)
	s_waitcnt lgkmcnt(0)
	s_cmp_gt_u32 s36, 0
	s_cbranch_scc1 .Lq0_i0
	v_mul_f32_e32 v14, v126, v34
	v_mul_f32_e32 v15, v126, v35
	v_mul_f32_e32 v16, v126, v36
	v_mul_f32_e32 v17, v126, v37
	v_pk_mul_f32 v[14:15], v[2:3], v[14:15]
	v_pk_mul_f32 v[16:17], v[4:5], v[16:17]
	v_pk_add_f32 v[6:7], v[6:7], v[14:15]
	v_pk_add_f32 v[8:9], v[8:9], v[16:17]
.Lq0_i0:
	s_cmp_gt_u32 s36, 1
	s_cbranch_scc1 .Lq0_i1
	v_mul_f32_e32 v14, v127, v38
	v_mul_f32_e32 v15, v127, v39
	v_mul_f32_e32 v16, v127, v40
	v_mul_f32_e32 v17, v127, v41
	v_pk_mul_f32 v[14:15], v[2:3], v[14:15]
	v_pk_mul_f32 v[16:17], v[4:5], v[16:17]
	v_pk_add_f32 v[6:7], v[6:7], v[14:15]
	v_pk_add_f32 v[8:9], v[8:9], v[16:17]
.Lq0_i1:
	s_cmp_gt_u32 s36, 2
	s_cbranch_scc1 .Lq0_i2
	v_mul_f32_e32 v14, v128, v42
	v_mul_f32_e32 v15, v128, v43
	v_mul_f32_e32 v16, v128, v44
	v_mul_f32_e32 v17, v128, v45
	v_pk_mul_f32 v[14:15], v[2:3], v[14:15]
	v_pk_mul_f32 v[16:17], v[4:5], v[16:17]
	v_pk_add_f32 v[6:7], v[6:7], v[14:15]
	v_pk_add_f32 v[8:9], v[8:9], v[16:17]
.Lq0_i2:
	s_cmp_gt_u32 s36, 3
	s_cbranch_scc1 .Lq0_i3
	v_mul_f32_e32 v14, v129, v46
	v_mul_f32_e32 v15, v129, v47
	v_mul_f32_e32 v16, v129, v48
	v_mul_f32_e32 v17, v129, v49
	v_pk_mul_f32 v[14:15], v[2:3], v[14:15]
	v_pk_mul_f32 v[16:17], v[4:5], v[16:17]
	v_pk_add_f32 v[6:7], v[6:7], v[14:15]
	v_pk_add_f32 v[8:9], v[8:9], v[16:17]
.Lq0_i3:
	s_cmp_gt_u32 s36, 4
	s_cbranch_scc1 .Lq0_i4
	v_mul_f32_e32 v14, v130, v50
	v_mul_f32_e32 v15, v130, v51
	v_mul_f32_e32 v16, v130, v52
	v_mul_f32_e32 v17, v130, v53
	v_pk_mul_f32 v[14:15], v[2:3], v[14:15]
	v_pk_mul_f32 v[16:17], v[4:5], v[16:17]
	v_pk_add_f32 v[6:7], v[6:7], v[14:15]
	v_pk_add_f32 v[8:9], v[8:9], v[16:17]
.Lq0_i4:
	s_cmp_gt_u32 s36, 5
	s_cbranch_scc1 .Lq0_i5
	v_mul_f32_e32 v14, v131, v54
	v_mul_f32_e32 v15, v131, v55
	v_mul_f32_e32 v16, v131, v56
	v_mul_f32_e32 v17, v131, v57
	v_pk_mul_f32 v[14:15], v[2:3], v[14:15]
	v_pk_mul_f32 v[16:17], v[4:5], v[16:17]
	v_pk_add_f32 v[6:7], v[6:7], v[14:15]
	v_pk_add_f32 v[8:9], v[8:9], v[16:17]
.Lq0_i5:
	s_cmp_gt_u32 s36, 6
	s_cbranch_scc1 .Lq0_i6
	v_mul_f32_e32 v14, v132, v58
	v_mul_f32_e32 v15, v132, v59
	v_mul_f32_e32 v16, v132, v60
	v_mul_f32_e32 v17, v132, v61
	v_pk_mul_f32 v[14:15], v[2:3], v[14:15]
	v_pk_mul_f32 v[16:17], v[4:5], v[16:17]
	v_pk_add_f32 v[6:7], v[6:7], v[14:15]
	v_pk_add_f32 v[8:9], v[8:9], v[16:17]
.Lq0_i6:
	s_cmp_gt_u32 s36, 7
	s_cbranch_scc1 .Lq0_i7
	v_mul_f32_e32 v14, v133, v62
	v_mul_f32_e32 v15, v133, v63
	v_mul_f32_e32 v16, v133, v64
	v_mul_f32_e32 v17, v133, v65
	v_pk_mul_f32 v[14:15], v[2:3], v[14:15]
	v_pk_mul_f32 v[16:17], v[4:5], v[16:17]
	v_pk_add_f32 v[6:7], v[6:7], v[14:15]
	v_pk_add_f32 v[8:9], v[8:9], v[16:17]
.Lq0_i7:
	s_cmp_gt_u32 s36, 8
	s_cbranch_scc1 .Lq0_i8
	v_mul_f32_e32 v14, v134, v66
	v_mul_f32_e32 v15, v134, v67
	v_mul_f32_e32 v16, v134, v68
	v_mul_f32_e32 v17, v134, v69
	v_pk_mul_f32 v[14:15], v[2:3], v[14:15]
	v_pk_mul_f32 v[16:17], v[4:5], v[16:17]
	v_pk_add_f32 v[6:7], v[6:7], v[14:15]
	v_pk_add_f32 v[8:9], v[8:9], v[16:17]
.Lq0_i8:
	s_cmp_gt_u32 s36, 9
	s_cbranch_scc1 .Lq0_i9
	v_mul_f32_e32 v14, v135, v70
	v_mul_f32_e32 v15, v135, v71
	v_mul_f32_e32 v16, v135, v72
	v_mul_f32_e32 v17, v135, v73
	v_pk_mul_f32 v[14:15], v[2:3], v[14:15]
	v_pk_mul_f32 v[16:17], v[4:5], v[16:17]
	v_pk_add_f32 v[6:7], v[6:7], v[14:15]
	v_pk_add_f32 v[8:9], v[8:9], v[16:17]
.Lq0_i9:
	s_cmp_gt_u32 s36, 10
	s_cbranch_scc1 .Lq0_i10
	v_mul_f32_e32 v14, v136, v74
	v_mul_f32_e32 v15, v136, v75
	v_mul_f32_e32 v16, v136, v76
	v_mul_f32_e32 v17, v136, v77
	v_pk_mul_f32 v[14:15], v[2:3], v[14:15]
	v_pk_mul_f32 v[16:17], v[4:5], v[16:17]
	v_pk_add_f32 v[6:7], v[6:7], v[14:15]
	v_pk_add_f32 v[8:9], v[8:9], v[16:17]
.Lq0_i10:
	s_cmp_gt_u32 s36, 11
	s_cbranch_scc1 .Lq0_i11
	v_mul_f32_e32 v14, v137, v78
	v_mul_f32_e32 v15, v137, v79
	v_mul_f32_e32 v16, v137, v80
	v_mul_f32_e32 v17, v137, v81
	v_pk_mul_f32 v[14:15], v[2:3], v[14:15]
	v_pk_mul_f32 v[16:17], v[4:5], v[16:17]
	v_pk_add_f32 v[6:7], v[6:7], v[14:15]
	v_pk_add_f32 v[8:9], v[8:9], v[16:17]
.Lq0_i11:
	s_cmp_gt_u32 s36, 12
	s_cbranch_scc1 .Lq0_i12
	v_mul_f32_e32 v14, v138, v82
	v_mul_f32_e32 v15, v138, v83
	v_mul_f32_e32 v16, v138, v84
	v_mul_f32_e32 v17, v138, v85
	v_pk_mul_f32 v[14:15], v[2:3], v[14:15]
	v_pk_mul_f32 v[16:17], v[4:5], v[16:17]
	v_pk_add_f32 v[6:7], v[6:7], v[14:15]
	v_pk_add_f32 v[8:9], v[8:9], v[16:17]
.Lq0_i12:
	s_cmp_gt_u32 s36, 13
	s_cbranch_scc1 .Lq0_i13
	v_mul_f32_e32 v14, v139, v86
	v_mul_f32_e32 v15, v139, v87
	v_mul_f32_e32 v16, v139, v88
	v_mul_f32_e32 v17, v139, v89
	v_pk_mul_f32 v[14:15], v[2:3], v[14:15]
	v_pk_mul_f32 v[16:17], v[4:5], v[16:17]
	v_pk_add_f32 v[6:7], v[6:7], v[14:15]
	v_pk_add_f32 v[8:9], v[8:9], v[16:17]
.Lq0_i13:
	s_cmp_gt_u32 s36, 14
	s_cbranch_scc1 .Lq0_i14
	v_mul_f32_e32 v14, v142, v90
	v_mul_f32_e32 v15, v142, v91
	v_mul_f32_e32 v16, v142, v92
	v_mul_f32_e32 v17, v142, v93
	v_pk_mul_f32 v[14:15], v[2:3], v[14:15]
	v_pk_mul_f32 v[16:17], v[4:5], v[16:17]
	v_pk_add_f32 v[6:7], v[6:7], v[14:15]
	v_pk_add_f32 v[8:9], v[8:9], v[16:17]
.Lq0_i14:
	global_load_dwordx4 v[34:37], v21, s[24:25]
	s_add_u32 s24, s24, 0x2000
	s_addc_u32 s25, s25, 0
	global_load_dwordx4 v[38:41], v21, s[24:25]
	s_add_u32 s24, s24, 0x2000
	s_addc_u32 s25, s25, 0
	global_load_dwordx4 v[42:45], v21, s[24:25]
	s_add_u32 s24, s24, 0x2000
	s_addc_u32 s25, s25, 0
	global_load_dwordx4 v[46:49], v21, s[24:25]
	s_add_u32 s24, s24, 0x2000
	s_addc_u32 s25, s25, 0
	s_cmp_gt_u32 s37, 4
	s_cselect_b64 s[20:21], s[16:17], s[26:27]
	global_load_dwordx4 v[50:53], v21, s[20:21]
	s_add_u32 s26, s26, 0x2000
	s_addc_u32 s27, s27, 0
	s_cmp_gt_u32 s37, 5
	s_cselect_b64 s[20:21], s[16:17], s[26:27]
	global_load_dwordx4 v[54:57], v21, s[20:21]
	s_add_u32 s26, s26, 0x2000
	s_addc_u32 s27, s27, 0
	s_cmp_gt_u32 s37, 6
	s_cselect_b64 s[20:21], s[16:17], s[26:27]
	global_load_dwordx4 v[58:61], v21, s[20:21]
	s_add_u32 s26, s26, 0x2000
	s_addc_u32 s27, s27, 0
	s_cmp_gt_u32 s37, 7
	s_cselect_b64 s[20:21], s[16:17], s[26:27]
	global_load_dwordx4 v[62:65], v21, s[20:21]
	s_add_u32 s26, s26, 0x2000
	s_addc_u32 s27, s27, 0
	ds_read_b32 v66, v25 offset:76
	ds_read_b32 v67, v25 offset:80
	ds_read_b32 v68, v25 offset:84
	ds_read_b32 v69, v25 offset:88
	ds_read_b32 v70, v26 offset:16
	ds_read_b32 v71, v26 offset:20
	ds_read_b32 v72, v26 offset:24
	ds_read_b32 v73, v26 offset:28
	v_mul_f32_e32 v10, v144, v94
	v_mul_f32_e32 v11, v144, v95
	v_mul_f32_e32 v12, v144, v96
	v_mul_f32_e32 v13, v144, v97
	v_pk_mul_f32 v[10:11], v[2:3], v[10:11]
	v_pk_mul_f32 v[12:13], v[4:5], v[12:13]
	v_pk_add_f32 v[6:7], v[6:7], v[10:11]
	v_pk_add_f32 v[8:9], v[8:9], v[12:13]
	s_cmp_gt_u32 s37, 0
	s_cbranch_scc0 .Lq0_n0
	v_mov_b32_e32 v18, 0x3f800000
	v_pk_fma_f32 v[14:15], v[6:7], v[18:19], v[10:11] op_sel_hi:[1,0,1] neg_lo:[0,0,1] neg_hi:[0,0,1]
	v_pk_fma_f32 v[16:17], v[8:9], v[18:19], v[12:13] op_sel_hi:[1,0,1] neg_lo:[0,0,1] neg_hi:[0,0,1]
	v_cvt_pk_bf16_f32 v14, v14, v15
	v_cvt_pk_bf16_f32 v15, v16, v17
	global_store_dwordx2 v22, v[14:15], s[28:29]
	s_branch .Lq0_d0
.Lq0_n0:
	v_mov_b32_e32 v18, v27
	v_pk_fma_f32 v[14:15], v[6:7], v[18:19], v[10:11] op_sel_hi:[1,0,1] neg_lo:[0,0,1] neg_hi:[0,0,1]
	v_pk_fma_f32 v[16:17], v[8:9], v[18:19], v[12:13] op_sel_hi:[1,0,1] neg_lo:[0,0,1] neg_hi:[0,0,1]
	v_cvt_pk_bf16_f32 v14, v14, v15
	v_cvt_pk_bf16_f32 v15, v16, v17
	global_store_dwordx2 v22, v[14:15], s[28:29]
	v_mul_f32_e32 v14, v148, v110
	v_mul_f32_e32 v15, v148, v111
	v_mul_f32_e32 v16, v148, v112
	v_mul_f32_e32 v17, v148, v113
	v_pk_mul_f32 v[14:15], v[2:3], v[14:15]
	v_pk_mul_f32 v[16:17], v[4:5], v[16:17]
	v_pk_add_f32 v[6:7], v[6:7], v[14:15] neg_lo:[0,1] neg_hi:[0,1]
	v_pk_add_f32 v[8:9], v[8:9], v[16:17] neg_lo:[0,1] neg_hi:[0,1]
.Lq0_d0:
	s_add_u32 s28, s28, 0x480
	s_addc_u32 s29, s29, 0
	v_mul_f32_e32 v10, v145, v98
	v_mul_f32_e32 v11, v145, v99
	v_mul_f32_e32 v12, v145, v100
	v_mul_f32_e32 v13, v145, v101
	v_pk_mul_f32 v[10:11], v[2:3], v[10:11]
	v_pk_mul_f32 v[12:13], v[4:5], v[12:13]
	v_pk_add_f32 v[6:7], v[6:7], v[10:11]
	v_pk_add_f32 v[8:9], v[8:9], v[12:13]
	s_cmp_gt_u32 s37, 1
	s_cbranch_scc0 .Lq0_n1
	v_mov_b32_e32 v18, 0x3f000000
	v_pk_fma_f32 v[14:15], v[6:7], v[18:19], v[10:11] op_sel_hi:[1,0,1] neg_lo:[0,0,1] neg_hi:[0,0,1]
	v_pk_fma_f32 v[16:17], v[8:9], v[18:19], v[12:13] op_sel_hi:[1,0,1] neg_lo:[0,0,1] neg_hi:[0,0,1]
	v_cvt_pk_bf16_f32 v14, v14, v15
	v_cvt_pk_bf16_f32 v15, v16, v17
	global_store_dwordx2 v22, v[14:15], s[28:29]
	s_branch .Lq0_d1
.Lq0_n1:
	v_mov_b32_e32 v18, v27
	v_pk_fma_f32 v[14:15], v[6:7], v[18:19], v[10:11] op_sel_hi:[1,0,1] neg_lo:[0,0,1] neg_hi:[0,0,1]
	v_pk_fma_f32 v[16:17], v[8:9], v[18:19], v[12:13] op_sel_hi:[1,0,1] neg_lo:[0,0,1] neg_hi:[0,0,1]
	v_cvt_pk_bf16_f32 v14, v14, v15
	v_cvt_pk_bf16_f32 v15, v16, v17
	global_store_dwordx2 v22, v[14:15], s[28:29]
	v_mul_f32_e32 v14, v149, v114
	v_mul_f32_e32 v15, v149, v115
	v_mul_f32_e32 v16, v149, v116
	v_mul_f32_e32 v17, v149, v117
	v_pk_mul_f32 v[14:15], v[2:3], v[14:15]
	v_pk_mul_f32 v[16:17], v[4:5], v[16:17]
	v_pk_add_f32 v[6:7], v[6:7], v[14:15] neg_lo:[0,1] neg_hi:[0,1]
	v_pk_add_f32 v[8:9], v[8:9], v[16:17] neg_lo:[0,1] neg_hi:[0,1]
.Lq0_d1:
	s_add_u32 s28, s28, 0x480
	s_addc_u32 s29, s29, 0
	v_mul_f32_e32 v10, v146, v102
	v_mul_f32_e32 v11, v146, v103
	v_mul_f32_e32 v12, v146, v104
	v_mul_f32_e32 v13, v146, v105
	v_pk_mul_f32 v[10:11], v[2:3], v[10:11]
	v_pk_mul_f32 v[12:13], v[4:5], v[12:13]
	v_pk_add_f32 v[6:7], v[6:7], v[10:11]
	v_pk_add_f32 v[8:9], v[8:9], v[12:13]
	s_cmp_gt_u32 s37, 2
	s_cbranch_scc0 .Lq0_n2
	v_mov_b32_e32 v18, 0x3eaaaaab
	v_pk_fma_f32 v[14:15], v[6:7], v[18:19], v[10:11] op_sel_hi:[1,0,1] neg_lo:[0,0,1] neg_hi:[0,0,1]
	v_pk_fma_f32 v[16:17], v[8:9], v[18:19], v[12:13] op_sel_hi:[1,0,1] neg_lo:[0,0,1] neg_hi:[0,0,1]
	v_cvt_pk_bf16_f32 v14, v14, v15
	v_cvt_pk_bf16_f32 v15, v16, v17
	global_store_dwordx2 v22, v[14:15], s[28:29]
	s_branch .Lq0_d2
.Lq0_n2:
	v_mov_b32_e32 v18, v27
	v_pk_fma_f32 v[14:15], v[6:7], v[18:19], v[10:11] op_sel_hi:[1,0,1] neg_lo:[0,0,1] neg_hi:[0,0,1]
	v_pk_fma_f32 v[16:17], v[8:9], v[18:19], v[12:13] op_sel_hi:[1,0,1] neg_lo:[0,0,1] neg_hi:[0,0,1]
	v_cvt_pk_bf16_f32 v14, v14, v15
	v_cvt_pk_bf16_f32 v15, v16, v17
	global_store_dwordx2 v22, v[14:15], s[28:29]
	v_mul_f32_e32 v14, v150, v118
	v_mul_f32_e32 v15, v150, v119
	v_mul_f32_e32 v16, v150, v120
	v_mul_f32_e32 v17, v150, v121
	v_pk_mul_f32 v[14:15], v[2:3], v[14:15]
	v_pk_mul_f32 v[16:17], v[4:5], v[16:17]
	v_pk_add_f32 v[6:7], v[6:7], v[14:15] neg_lo:[0,1] neg_hi:[0,1]
	v_pk_add_f32 v[8:9], v[8:9], v[16:17] neg_lo:[0,1] neg_hi:[0,1]
.Lq0_d2:
	s_add_u32 s28, s28, 0x480
	s_addc_u32 s29, s29, 0
	v_mul_f32_e32 v10, v147, v106
	v_mul_f32_e32 v11, v147, v107
	v_mul_f32_e32 v12, v147, v108
	v_mul_f32_e32 v13, v147, v109
	v_pk_mul_f32 v[10:11], v[2:3], v[10:11]
	v_pk_mul_f32 v[12:13], v[4:5], v[12:13]
	v_pk_add_f32 v[6:7], v[6:7], v[10:11]
	v_pk_add_f32 v[8:9], v[8:9], v[12:13]
	s_cmp_gt_u32 s37, 3
	s_cbranch_scc0 .Lq0_n3
	v_mov_b32_e32 v18, 0x3e800000
	v_pk_fma_f32 v[14:15], v[6:7], v[18:19], v[10:11] op_sel_hi:[1,0,1] neg_lo:[0,0,1] neg_hi:[0,0,1]
	v_pk_fma_f32 v[16:17], v[8:9], v[18:19], v[12:13] op_sel_hi:[1,0,1] neg_lo:[0,0,1] neg_hi:[0,0,1]
	v_cvt_pk_bf16_f32 v14, v14, v15
	v_cvt_pk_bf16_f32 v15, v16, v17
	global_store_dwordx2 v22, v[14:15], s[28:29]
	s_branch .Lq0_d3
.Lq0_n3:
	v_mov_b32_e32 v18, v27
	v_pk_fma_f32 v[14:15], v[6:7], v[18:19], v[10:11] op_sel_hi:[1,0,1] neg_lo:[0,0,1] neg_hi:[0,0,1]
	v_pk_fma_f32 v[16:17], v[8:9], v[18:19], v[12:13] op_sel_hi:[1,0,1] neg_lo:[0,0,1] neg_hi:[0,0,1]
	v_cvt_pk_bf16_f32 v14, v14, v15
	v_cvt_pk_bf16_f32 v15, v16, v17
	global_store_dwordx2 v22, v[14:15], s[28:29]
	v_mul_f32_e32 v14, v151, v122
	v_mul_f32_e32 v15, v151, v123
	v_mul_f32_e32 v16, v151, v124
	v_mul_f32_e32 v17, v151, v125
	v_pk_mul_f32 v[14:15], v[2:3], v[14:15]
	v_pk_mul_f32 v[16:17], v[4:5], v[16:17]
	v_pk_add_f32 v[6:7], v[6:7], v[14:15] neg_lo:[0,1] neg_hi:[0,1]
	v_pk_add_f32 v[8:9], v[8:9], v[16:17] neg_lo:[0,1] neg_hi:[0,1]
.Lq0_d3:
	s_add_u32 s28, s28, 0x480
	s_addc_u32 s29, s29, 0
	global_load_dwordx4 v[94:97], v21, s[24:25]
	s_add_u32 s24, s24, 0x2000
	s_addc_u32 s25, s25, 0
	global_load_dwordx4 v[98:101], v21, s[24:25]
	s_add_u32 s24, s24, 0x2000
	s_addc_u32 s25, s25, 0
	global_load_dwordx4 v[102:105], v21, s[24:25]
	s_add_u32 s24, s24, 0x2000
	s_addc_u32 s25, s25, 0
	global_load_dwordx4 v[106:109], v21, s[24:25]
	s_add_u32 s24, s24, 0x2000
	s_addc_u32 s25, s25, 0
	s_cmp_gt_u32 s37, 8
	s_cselect_b64 s[20:21], s[16:17], s[26:27]
	global_load_dwordx4 v[110:113], v21, s[20:21]
	s_add_u32 s26, s26, 0x2000
	s_addc_u32 s27, s27, 0
	s_cmp_gt_u32 s37, 9
	s_cselect_b64 s[20:21], s[16:17], s[26:27]
	global_load_dwordx4 v[114:117], v21, s[20:21]
	s_add_u32 s26, s26, 0x2000
	s_addc_u32 s27, s27, 0
	s_cmp_gt_u32 s37, 10
	s_cselect_b64 s[20:21], s[16:17], s[26:27]
	global_load_dwordx4 v[118:121], v21, s[20:21]
	s_add_u32 s26, s26, 0x2000
	s_addc_u32 s27, s27, 0
	s_cmp_gt_u32 s37, 11
	s_cselect_b64 s[20:21], s[16:17], s[26:27]
	global_load_dwordx4 v[122:125], v21, s[20:21]
	s_add_u32 s26, s26, 0x2000
	s_addc_u32 s27, s27, 0
	ds_read_b32 v144, v25 offset:92
	ds_read_b32 v145, v25 offset:96
	ds_read_b32 v146, v25 offset:100
	ds_read_b32 v147, v25 offset:104
	ds_read_b32 v148, v26 offset:32
	ds_read_b32 v149, v26 offset:36
	ds_read_b32 v150, v26 offset:40
	ds_read_b32 v151, v26 offset:44
	s_waitcnt vmcnt(12)
	s_waitcnt lgkmcnt(0)
	v_mul_f32_e32 v10, v66, v34
	v_mul_f32_e32 v11, v66, v35
	v_mul_f32_e32 v12, v66, v36
	v_mul_f32_e32 v13, v66, v37
	v_pk_mul_f32 v[10:11], v[2:3], v[10:11]
	v_pk_mul_f32 v[12:13], v[4:5], v[12:13]
	v_pk_add_f32 v[6:7], v[6:7], v[10:11]
	v_pk_add_f32 v[8:9], v[8:9], v[12:13]
	s_cmp_gt_u32 s37, 4
	s_cbranch_scc0 .Lq0_n4
	v_mov_b32_e32 v18, 0x3e4ccccd
	v_pk_fma_f32 v[14:15], v[6:7], v[18:19], v[10:11] op_sel_hi:[1,0,1] neg_lo:[0,0,1] neg_hi:[0,0,1]
	v_pk_fma_f32 v[16:17], v[8:9], v[18:19], v[12:13] op_sel_hi:[1,0,1] neg_lo:[0,0,1] neg_hi:[0,0,1]
	v_cvt_pk_bf16_f32 v14, v14, v15
	v_cvt_pk_bf16_f32 v15, v16, v17
	global_store_dwordx2 v22, v[14:15], s[28:29]
	s_branch .Lq0_d4
.Lq0_n4:
	v_mov_b32_e32 v18, v27
	v_pk_fma_f32 v[14:15], v[6:7], v[18:19], v[10:11] op_sel_hi:[1,0,1] neg_lo:[0,0,1] neg_hi:[0,0,1]
	v_pk_fma_f32 v[16:17], v[8:9], v[18:19], v[12:13] op_sel_hi:[1,0,1] neg_lo:[0,0,1] neg_hi:[0,0,1]
	v_cvt_pk_bf16_f32 v14, v14, v15
	v_cvt_pk_bf16_f32 v15, v16, v17
	global_store_dwordx2 v22, v[14:15], s[28:29]
	v_mul_f32_e32 v14, v70, v50
	v_mul_f32_e32 v15, v70, v51
	v_mul_f32_e32 v16, v70, v52
	v_mul_f32_e32 v17, v70, v53
	v_pk_mul_f32 v[14:15], v[2:3], v[14:15]
	v_pk_mul_f32 v[16:17], v[4:5], v[16:17]
	v_pk_add_f32 v[6:7], v[6:7], v[14:15] neg_lo:[0,1] neg_hi:[0,1]
	v_pk_add_f32 v[8:9], v[8:9], v[16:17] neg_lo:[0,1] neg_hi:[0,1]
.Lq0_d4:
	s_add_u32 s28, s28, 0x480
	s_addc_u32 s29, s29, 0
	v_mul_f32_e32 v10, v67, v38
	v_mul_f32_e32 v11, v67, v39
	v_mul_f32_e32 v12, v67, v40
	v_mul_f32_e32 v13, v67, v41
	v_pk_mul_f32 v[10:11], v[2:3], v[10:11]
	v_pk_mul_f32 v[12:13], v[4:5], v[12:13]
	v_pk_add_f32 v[6:7], v[6:7], v[10:11]
	v_pk_add_f32 v[8:9], v[8:9], v[12:13]
	s_cmp_gt_u32 s37, 5
	s_cbranch_scc0 .Lq0_n5
	v_mov_b32_e32 v18, 0x3e2aaaab
	v_pk_fma_f32 v[14:15], v[6:7], v[18:19], v[10:11] op_sel_hi:[1,0,1] neg_lo:[0,0,1] neg_hi:[0,0,1]
	v_pk_fma_f32 v[16:17], v[8:9], v[18:19], v[12:13] op_sel_hi:[1,0,1] neg_lo:[0,0,1] neg_hi:[0,0,1]
	v_cvt_pk_bf16_f32 v14, v14, v15
	v_cvt_pk_bf16_f32 v15, v16, v17
	global_store_dwordx2 v22, v[14:15], s[28:29]
	s_branch .Lq0_d5
.Lq0_n5:
	v_mov_b32_e32 v18, v27
	v_pk_fma_f32 v[14:15], v[6:7], v[18:19], v[10:11] op_sel_hi:[1,0,1] neg_lo:[0,0,1] neg_hi:[0,0,1]
	v_pk_fma_f32 v[16:17], v[8:9], v[18:19], v[12:13] op_sel_hi:[1,0,1] neg_lo:[0,0,1] neg_hi:[0,0,1]
	v_cvt_pk_bf16_f32 v14, v14, v15
	v_cvt_pk_bf16_f32 v15, v16, v17
	global_store_dwordx2 v22, v[14:15], s[28:29]
	v_mul_f32_e32 v14, v71, v54
	v_mul_f32_e32 v15, v71, v55
	v_mul_f32_e32 v16, v71, v56
	v_mul_f32_e32 v17, v71, v57
	v_pk_mul_f32 v[14:15], v[2:3], v[14:15]
	v_pk_mul_f32 v[16:17], v[4:5], v[16:17]
	v_pk_add_f32 v[6:7], v[6:7], v[14:15] neg_lo:[0,1] neg_hi:[0,1]
	v_pk_add_f32 v[8:9], v[8:9], v[16:17] neg_lo:[0,1] neg_hi:[0,1]
.Lq0_d5:
	s_add_u32 s28, s28, 0x480
	s_addc_u32 s29, s29, 0
	v_mul_f32_e32 v10, v68, v42
	v_mul_f32_e32 v11, v68, v43
	v_mul_f32_e32 v12, v68, v44
	v_mul_f32_e32 v13, v68, v45
	v_pk_mul_f32 v[10:11], v[2:3], v[10:11]
	v_pk_mul_f32 v[12:13], v[4:5], v[12:13]
	v_pk_add_f32 v[6:7], v[6:7], v[10:11]
	v_pk_add_f32 v[8:9], v[8:9], v[12:13]
	s_cmp_gt_u32 s37, 6
	s_cbranch_scc0 .Lq0_n6
	v_mov_b32_e32 v18, 0x3e124925
	v_pk_fma_f32 v[14:15], v[6:7], v[18:19], v[10:11] op_sel_hi:[1,0,1] neg_lo:[0,0,1] neg_hi:[0,0,1]
	v_pk_fma_f32 v[16:17], v[8:9], v[18:19], v[12:13] op_sel_hi:[1,0,1] neg_lo:[0,0,1] neg_hi:[0,0,1]
	v_cvt_pk_bf16_f32 v14, v14, v15
	v_cvt_pk_bf16_f32 v15, v16, v17
	global_store_dwordx2 v22, v[14:15], s[28:29]
	s_branch .Lq0_d6
.Lq0_n6:
	v_mov_b32_e32 v18, v27
	v_pk_fma_f32 v[14:15], v[6:7], v[18:19], v[10:11] op_sel_hi:[1,0,1] neg_lo:[0,0,1] neg_hi:[0,0,1]
	v_pk_fma_f32 v[16:17], v[8:9], v[18:19], v[12:13] op_sel_hi:[1,0,1] neg_lo:[0,0,1] neg_hi:[0,0,1]
	v_cvt_pk_bf16_f32 v14, v14, v15
	v_cvt_pk_bf16_f32 v15, v16, v17
	global_store_dwordx2 v22, v[14:15], s[28:29]
	v_mul_f32_e32 v14, v72, v58
	v_mul_f32_e32 v15, v72, v59
	v_mul_f32_e32 v16, v72, v60
	v_mul_f32_e32 v17, v72, v61
	v_pk_mul_f32 v[14:15], v[2:3], v[14:15]
	v_pk_mul_f32 v[16:17], v[4:5], v[16:17]
	v_pk_add_f32 v[6:7], v[6:7], v[14:15] neg_lo:[0,1] neg_hi:[0,1]
	v_pk_add_f32 v[8:9], v[8:9], v[16:17] neg_lo:[0,1] neg_hi:[0,1]
.Lq0_d6:
	s_add_u32 s28, s28, 0x480
	s_addc_u32 s29, s29, 0
	v_mul_f32_e32 v10, v69, v46
	v_mul_f32_e32 v11, v69, v47
	v_mul_f32_e32 v12, v69, v48
	v_mul_f32_e32 v13, v69, v49
	v_pk_mul_f32 v[10:11], v[2:3], v[10:11]
	v_pk_mul_f32 v[12:13], v[4:5], v[12:13]
	v_pk_add_f32 v[6:7], v[6:7], v[10:11]
	v_pk_add_f32 v[8:9], v[8:9], v[12:13]
	s_cmp_gt_u32 s37, 7
	s_cbranch_scc0 .Lq0_n7
	v_mov_b32_e32 v18, 0x3e000000
	v_pk_fma_f32 v[14:15], v[6:7], v[18:19], v[10:11] op_sel_hi:[1,0,1] neg_lo:[0,0,1] neg_hi:[0,0,1]
	v_pk_fma_f32 v[16:17], v[8:9], v[18:19], v[12:13] op_sel_hi:[1,0,1] neg_lo:[0,0,1] neg_hi:[0,0,1]
	v_cvt_pk_bf16_f32 v14, v14, v15
	v_cvt_pk_bf16_f32 v15, v16, v17
	global_store_dwordx2 v22, v[14:15], s[28:29]
	s_branch .Lq0_d7
.Lq0_n7:
	v_mov_b32_e32 v18, v27
	v_pk_fma_f32 v[14:15], v[6:7], v[18:19], v[10:11] op_sel_hi:[1,0,1] neg_lo:[0,0,1] neg_hi:[0,0,1]
	v_pk_fma_f32 v[16:17], v[8:9], v[18:19], v[12:13] op_sel_hi:[1,0,1] neg_lo:[0,0,1] neg_hi:[0,0,1]
	v_cvt_pk_bf16_f32 v14, v14, v15
	v_cvt_pk_bf16_f32 v15, v16, v17
	global_store_dwordx2 v22, v[14:15], s[28:29]
	v_mul_f32_e32 v14, v73, v62
	v_mul_f32_e32 v15, v73, v63
	v_mul_f32_e32 v16, v73, v64
	v_mul_f32_e32 v17, v73, v65
	v_pk_mul_f32 v[14:15], v[2:3], v[14:15]
	v_pk_mul_f32 v[16:17], v[4:5], v[16:17]
	v_pk_add_f32 v[6:7], v[6:7], v[14:15] neg_lo:[0,1] neg_hi:[0,1]
	v_pk_add_f32 v[8:9], v[8:9], v[16:17] neg_lo:[0,1] neg_hi:[0,1]
.Lq0_d7:
	s_add_u32 s28, s28, 0x480
	s_addc_u32 s29, s29, 0
	global_load_dwordx4 v[34:37], v21, s[24:25]
	s_add_u32 s24, s24, 0x2000
	s_addc_u32 s25, s25, 0
	global_load_dwordx4 v[38:41], v21, s[24:25]
	s_add_u32 s24, s24, 0x2000
	s_addc_u32 s25, s25, 0
	global_load_dwordx4 v[42:45], v21, s[24:25]
	s_add_u32 s24, s24, 0x2000
	s_addc_u32 s25, s25, 0
	global_load_dwordx4 v[46:49], v21, s[24:25]
	s_add_u32 s24, s24, 0x2000
	s_addc_u32 s25, s25, 0
	s_cmp_gt_u32 s37, 12
	s_cselect_b64 s[20:21], s[16:17], s[26:27]
	global_load_dwordx4 v[50:53], v21, s[20:21]
	s_add_u32 s26, s26, 0x2000
	s_addc_u32 s27, s27, 0
	s_cmp_gt_u32 s37, 13
	s_cselect_b64 s[20:21], s[16:17], s[26:27]
	global_load_dwordx4 v[54:57], v21, s[20:21]
	s_add_u32 s26, s26, 0x2000
	s_addc_u32 s27, s27, 0
	s_cmp_gt_u32 s37, 14
	s_cselect_b64 s[20:21], s[16:17], s[26:27]
	global_load_dwordx4 v[58:61], v21, s[20:21]
	s_add_u32 s26, s26, 0x2000
	s_addc_u32 s27, s27, 0
	global_load_dwordx4 v[62:65], v21, s[26:27]
	s_add_u32 s26, s26, 0x2000
	s_addc_u32 s27, s27, 0
	ds_read_b32 v66, v25 offset:108
	ds_read_b32 v67, v25 offset:112
	ds_read_b32 v68, v25 offset:116
	ds_read_b32 v69, v25 offset:120
	ds_read_b32 v70, v26 offset:48
	ds_read_b32 v71, v26 offset:52
	ds_read_b32 v72, v26 offset:56
	ds_read_b32 v73, v26 offset:60
	s_waitcnt vmcnt(12)
	s_waitcnt lgkmcnt(0)
	v_mul_f32_e32 v10, v144, v94
	v_mul_f32_e32 v11, v144, v95
	v_mul_f32_e32 v12, v144, v96
	v_mul_f32_e32 v13, v144, v97
	v_pk_mul_f32 v[10:11], v[2:3], v[10:11]
	v_pk_mul_f32 v[12:13], v[4:5], v[12:13]
	v_pk_add_f32 v[6:7], v[6:7], v[10:11]
	v_pk_add_f32 v[8:9], v[8:9], v[12:13]
	s_cmp_gt_u32 s37, 8
	s_cbranch_scc0 .Lq0_n8
	v_mov_b32_e32 v18, 0x3de38e39
	v_pk_fma_f32 v[14:15], v[6:7], v[18:19], v[10:11] op_sel_hi:[1,0,1] neg_lo:[0,0,1] neg_hi:[0,0,1]
	v_pk_fma_f32 v[16:17], v[8:9], v[18:19], v[12:13] op_sel_hi:[1,0,1] neg_lo:[0,0,1] neg_hi:[0,0,1]
	v_cvt_pk_bf16_f32 v14, v14, v15
	v_cvt_pk_bf16_f32 v15, v16, v17
	global_store_dwordx2 v22, v[14:15], s[28:29]
	s_branch .Lq0_d8

.Lq0_d8:
	s_add_u32 s28, s28, 0x480
	s_addc_u32 s29, s29, 0
	v_mul_f32_e32 v10, v145, v98
	v_mul_f32_e32 v11, v145, v99
	v_mul_f32_e32 v12, v145, v100
	v_mul_f32_e32 v13, v145, v101
	v_pk_mul_f32 v[10:11], v[2:3], v[10:11]
	v_pk_mul_f32 v[12:13], v[4:5], v[12:13]
	v_pk_add_f32 v[6:7], v[6:7], v[10:11]
	v_pk_add_f32 v[8:9], v[8:9], v[12:13]
	s_cmp_gt_u32 s37, 9
	s_cbranch_scc0 .Lq0_n9
	v_mov_b32_e32 v18, 0x3dcccccd
	v_pk_fma_f32 v[14:15], v[6:7], v[18:19], v[10:11] op_sel_hi:[1,0,1] neg_lo:[0,0,1] neg_hi:[0,0,1]
	v_pk_fma_f32 v[16:17], v[8:9], v[18:19], v[12:13] op_sel_hi:[1,0,1] neg_lo:[0,0,1] neg_hi:[0,0,1]
	v_cvt_pk_bf16_f32 v14, v14, v15
	v_cvt_pk_bf16_f32 v15, v16, v17
	global_store_dwordx2 v22, v[14:15], s[28:29]
	s_branch .Lq0_d9

.Lq0_d9:
	s_add_u32 s28, s28, 0x480
	s_addc_u32 s29, s29, 0
	v_mul_f32_e32 v10, v146, v102
	v_mul_f32_e32 v11, v146, v103
	v_mul_f32_e32 v12, v146, v104
	v_mul_f32_e32 v13, v146, v105
	v_pk_mul_f32 v[10:11], v[2:3], v[10:11]
	v_pk_mul_f32 v[12:13], v[4:5], v[12:13]
	v_pk_add_f32 v[6:7], v[6:7], v[10:11]
	v_pk_add_f32 v[8:9], v[8:9], v[12:13]
	s_cmp_gt_u32 s37, 10
	s_cbranch_scc0 .Lq0_n10
	v_mov_b32_e32 v18, 0x3dba2e8c
	v_pk_fma_f32 v[14:15], v[6:7], v[18:19], v[10:11] op_sel_hi:[1,0,1] neg_lo:[0,0,1] neg_hi:[0,0,1]
	v_pk_fma_f32 v[16:17], v[8:9], v[18:19], v[12:13] op_sel_hi:[1,0,1] neg_lo:[0,0,1] neg_hi:[0,0,1]
	v_cvt_pk_bf16_f32 v14, v14, v15
	v_cvt_pk_bf16_f32 v15, v16, v17
	global_store_dwordx2 v22, v[14:15], s[28:29]
	s_branch .Lq0_d10

.Lq0_d10:
	s_add_u32 s28, s28, 0x480
	s_addc_u32 s29, s29, 0
	v_mul_f32_e32 v10, v147, v106
	v_mul_f32_e32 v11, v147, v107
	v_mul_f32_e32 v12, v147, v108
	v_mul_f32_e32 v13, v147, v109
	v_pk_mul_f32 v[10:11], v[2:3], v[10:11]
	v_pk_mul_f32 v[12:13], v[4:5], v[12:13]
	v_pk_add_f32 v[6:7], v[6:7], v[10:11]
	v_pk_add_f32 v[8:9], v[8:9], v[12:13]
	s_cmp_gt_u32 s37, 11
	s_cbranch_scc0 .Lq0_n11
	v_mov_b32_e32 v18, 0x3daaaaab
	v_pk_fma_f32 v[14:15], v[6:7], v[18:19], v[10:11] op_sel_hi:[1,0,1] neg_lo:[0,0,1] neg_hi:[0,0,1]
	v_pk_fma_f32 v[16:17], v[8:9], v[18:19], v[12:13] op_sel_hi:[1,0,1] neg_lo:[0,0,1] neg_hi:[0,0,1]
	v_cvt_pk_bf16_f32 v14, v14, v15
	v_cvt_pk_bf16_f32 v15, v16, v17
	global_store_dwordx2 v22, v[14:15], s[28:29]
	s_branch .Lq0_d11

.Lq0_d11:
	s_add_u32 s28, s28, 0x480
	s_addc_u32 s29, s29, 0
	global_load_dwordx4 v[94:97], v21, s[24:25]
	s_add_u32 s24, s24, 0x2000
	s_addc_u32 s25, s25, 0
	global_load_dwordx4 v[98:101], v21, s[24:25]
	s_add_u32 s24, s24, 0x2000
	s_addc_u32 s25, s25, 0
	global_load_dwordx4 v[102:105], v21, s[24:25]
	s_add_u32 s24, s24, 0x2000
	s_addc_u32 s25, s25, 0
	global_load_dwordx4 v[106:109], v21, s[24:25]
	s_add_u32 s24, s24, 0x2000
	s_addc_u32 s25, s25, 0
	global_load_dwordx4 v[110:113], v21, s[26:27]
	s_add_u32 s26, s26, 0x2000
	s_addc_u32 s27, s27, 0
	global_load_dwordx4 v[114:117], v21, s[26:27]
	s_add_u32 s26, s26, 0x2000
	s_addc_u32 s27, s27, 0
	global_load_dwordx4 v[118:121], v21, s[26:27]
	s_add_u32 s26, s26, 0x2000
	s_addc_u32 s27, s27, 0
	global_load_dwordx4 v[122:125], v21, s[26:27]
	s_add_u32 s26, s26, 0x2000
	s_addc_u32 s27, s27, 0
	ds_read_b32 v144, v25 offset:124
	ds_read_b32 v145, v25 offset:128
	ds_read_b32 v146, v25 offset:132
	ds_read_b32 v147, v25 offset:136
	ds_read_b32 v148, v26 offset:64
	ds_read_b32 v149, v26 offset:68
	ds_read_b32 v150, v26 offset:72
	ds_read_b32 v151, v26 offset:76
	s_waitcnt vmcnt(12)
	s_waitcnt lgkmcnt(0)
	v_mul_f32_e32 v10, v66, v34
	v_mul_f32_e32 v11, v66, v35
	v_mul_f32_e32 v12, v66, v36
	v_mul_f32_e32 v13, v66, v37
	v_pk_mul_f32 v[10:11], v[2:3], v[10:11]
	v_pk_mul_f32 v[12:13], v[4:5], v[12:13]
	v_pk_add_f32 v[6:7], v[6:7], v[10:11]
	v_pk_add_f32 v[8:9], v[8:9], v[12:13]
	s_cmp_gt_u32 s37, 12
	s_cbranch_scc0 .Lq0_n12
	v_mov_b32_e32 v18, 0x3d9d89d9
	v_pk_fma_f32 v[14:15], v[6:7], v[18:19], v[10:11] op_sel_hi:[1,0,1] neg_lo:[0,0,1] neg_hi:[0,0,1]
	v_pk_fma_f32 v[16:17], v[8:9], v[18:19], v[12:13] op_sel_hi:[1,0,1] neg_lo:[0,0,1] neg_hi:[0,0,1]
	v_cvt_pk_bf16_f32 v14, v14, v15
	v_cvt_pk_bf16_f32 v15, v16, v17
	global_store_dwordx2 v22, v[14:15], s[28:29]
	s_branch .Lq0_d12

.Lq0_d12:
	s_add_u32 s28, s28, 0x480
	s_addc_u32 s29, s29, 0
	v_mul_f32_e32 v10, v67, v38
	v_mul_f32_e32 v11, v67, v39
	v_mul_f32_e32 v12, v67, v40
	v_mul_f32_e32 v13, v67, v41
	v_pk_mul_f32 v[10:11], v[2:3], v[10:11]
	v_pk_mul_f32 v[12:13], v[4:5], v[12:13]
	v_pk_add_f32 v[6:7], v[6:7], v[10:11]
	v_pk_add_f32 v[8:9], v[8:9], v[12:13]
	s_cmp_gt_u32 s37, 13
	s_cbranch_scc0 .Lq0_n13
	v_mov_b32_e32 v18, 0x3d924925
	v_pk_fma_f32 v[14:15], v[6:7], v[18:19], v[10:11] op_sel_hi:[1,0,1] neg_lo:[0,0,1] neg_hi:[0,0,1]
	v_pk_fma_f32 v[16:17], v[8:9], v[18:19], v[12:13] op_sel_hi:[1,0,1] neg_lo:[0,0,1] neg_hi:[0,0,1]
	v_cvt_pk_bf16_f32 v14, v14, v15
	v_cvt_pk_bf16_f32 v15, v16, v17
	global_store_dwordx2 v22, v[14:15], s[28:29]
	s_branch .Lq0_d13

.Lq0_d13:
	s_add_u32 s28, s28, 0x480
	s_addc_u32 s29, s29, 0
	v_mul_f32_e32 v10, v68, v42
	v_mul_f32_e32 v11, v68, v43
	v_mul_f32_e32 v12, v68, v44
	v_mul_f32_e32 v13, v68, v45
	v_pk_mul_f32 v[10:11], v[2:3], v[10:11]
	v_pk_mul_f32 v[12:13], v[4:5], v[12:13]
	v_pk_add_f32 v[6:7], v[6:7], v[10:11]
	v_pk_add_f32 v[8:9], v[8:9], v[12:13]
	s_cmp_gt_u32 s37, 14
	s_cbranch_scc0 .Lq0_n14
	v_mov_b32_e32 v18, 0x3d888889
	v_pk_fma_f32 v[14:15], v[6:7], v[18:19], v[10:11] op_sel_hi:[1,0,1] neg_lo:[0,0,1] neg_hi:[0,0,1]
	v_pk_fma_f32 v[16:17], v[8:9], v[18:19], v[12:13] op_sel_hi:[1,0,1] neg_lo:[0,0,1] neg_hi:[0,0,1]
	v_cvt_pk_bf16_f32 v14, v14, v15
	v_cvt_pk_bf16_f32 v15, v16, v17
	global_store_dwordx2 v22, v[14:15], s[28:29]
	s_branch .Lq0_d14

.Lq0_d14:
	s_add_u32 s28, s28, 0x480
	s_addc_u32 s29, s29, 0
	v_mul_f32_e32 v10, v69, v46
	v_mul_f32_e32 v11, v69, v47
	v_mul_f32_e32 v12, v69, v48
	v_mul_f32_e32 v13, v69, v49
	v_pk_mul_f32 v[10:11], v[2:3], v[10:11]
	v_pk_mul_f32 v[12:13], v[4:5], v[12:13]
	v_pk_add_f32 v[6:7], v[6:7], v[10:11]
	v_pk_add_f32 v[8:9], v[8:9], v[12:13]
	v_mov_b32_e32 v18, v27
	v_pk_fma_f32 v[14:15], v[6:7], v[18:19], v[10:11] op_sel_hi:[1,0,1] neg_lo:[0,0,1] neg_hi:[0,0,1]
	v_pk_fma_f32 v[16:17], v[8:9], v[18:19], v[12:13] op_sel_hi:[1,0,1] neg_lo:[0,0,1] neg_hi:[0,0,1]
	v_cvt_pk_bf16_f32 v14, v14, v15
	v_cvt_pk_bf16_f32 v15, v16, v17
	global_store_dwordx2 v22, v[14:15], s[28:29]
	v_mul_f32_e32 v14, v73, v62
	v_mul_f32_e32 v15, v73, v63
	v_mul_f32_e32 v16, v73, v64
	v_mul_f32_e32 v17, v73, v65
	v_pk_mul_f32 v[14:15], v[2:3], v[14:15]
	v_pk_mul_f32 v[16:17], v[4:5], v[16:17]
	v_pk_add_f32 v[6:7], v[6:7], v[14:15] neg_lo:[0,1] neg_hi:[0,1]
	v_pk_add_f32 v[8:9], v[8:9], v[16:17] neg_lo:[0,1] neg_hi:[0,1]
	s_add_u32 s28, s28, 0x480
	s_addc_u32 s29, s29, 0
	global_load_dwordx4 v[34:37], v21, s[24:25]
	s_add_u32 s24, s24, 0x2000
	s_addc_u32 s25, s25, 0
	global_load_dwordx4 v[38:41], v21, s[24:25]
	s_add_u32 s24, s24, 0x2000
	s_addc_u32 s25, s25, 0
	global_load_dwordx4 v[42:45], v21, s[24:25]
	s_add_u32 s24, s24, 0x2000
	s_addc_u32 s25, s25, 0
	global_load_dwordx4 v[46:49], v21, s[24:25]
	s_add_u32 s24, s24, 0x2000
	s_addc_u32 s25, s25, 0
	global_load_dwordx4 v[50:53], v21, s[26:27]
	s_add_u32 s26, s26, 0x2000
	s_addc_u32 s27, s27, 0
	global_load_dwordx4 v[54:57], v21, s[26:27]
	s_add_u32 s26, s26, 0x2000
	s_addc_u32 s27, s27, 0
	global_load_dwordx4 v[58:61], v21, s[26:27]
	s_add_u32 s26, s26, 0x2000
	s_addc_u32 s27, s27, 0
	global_load_dwordx4 v[62:65], v21, s[26:27]
	s_add_u32 s26, s26, 0x2000
	s_addc_u32 s27, s27, 0
	ds_read_b32 v66, v25 offset:140
	ds_read_b32 v67, v25 offset:144
	ds_read_b32 v68, v25 offset:148
	ds_read_b32 v69, v25 offset:152
	ds_read_b32 v70, v26 offset:80
	ds_read_b32 v71, v26 offset:84
	ds_read_b32 v72, v26 offset:88
	ds_read_b32 v73, v26 offset:92
	s_waitcnt vmcnt(12)
	s_waitcnt lgkmcnt(0)
	v_mul_f32_e32 v10, v144, v94
	v_mul_f32_e32 v11, v144, v95
	v_mul_f32_e32 v12, v144, v96
	v_mul_f32_e32 v13, v144, v97
	v_pk_mul_f32 v[10:11], v[2:3], v[10:11]
	v_pk_mul_f32 v[12:13], v[4:5], v[12:13]
	v_pk_add_f32 v[6:7], v[6:7], v[10:11]
	v_pk_add_f32 v[8:9], v[8:9], v[12:13]
	v_mov_b32_e32 v18, v27
	v_pk_fma_f32 v[14:15], v[6:7], v[18:19], v[10:11] op_sel_hi:[1,0,1] neg_lo:[0,0,1] neg_hi:[0,0,1]
	v_pk_fma_f32 v[16:17], v[8:9], v[18:19], v[12:13] op_sel_hi:[1,0,1] neg_lo:[0,0,1] neg_hi:[0,0,1]
	v_cvt_pk_bf16_f32 v14, v14, v15
	v_cvt_pk_bf16_f32 v15, v16, v17
	global_store_dwordx2 v22, v[14:15], s[28:29]
	v_mul_f32_e32 v14, v148, v110
	v_mul_f32_e32 v15, v148, v111
	v_mul_f32_e32 v16, v148, v112
	v_mul_f32_e32 v17, v148, v113
	v_pk_mul_f32 v[14:15], v[2:3], v[14:15]
	v_pk_mul_f32 v[16:17], v[4:5], v[16:17]
	v_pk_add_f32 v[6:7], v[6:7], v[14:15] neg_lo:[0,1] neg_hi:[0,1]
	v_pk_add_f32 v[8:9], v[8:9], v[16:17] neg_lo:[0,1] neg_hi:[0,1]
	s_add_u32 s28, s28, 0x480
	s_addc_u32 s29, s29, 0
	v_mul_f32_e32 v10, v145, v98
	v_mul_f32_e32 v11, v145, v99
	v_mul_f32_e32 v12, v145, v100
	v_mul_f32_e32 v13, v145, v101
	v_pk_mul_f32 v[10:11], v[2:3], v[10:11]
	v_pk_mul_f32 v[12:13], v[4:5], v[12:13]
	v_pk_add_f32 v[6:7], v[6:7], v[10:11]
	v_pk_add_f32 v[8:9], v[8:9], v[12:13]
	v_mov_b32_e32 v18, v27
	v_pk_fma_f32 v[14:15], v[6:7], v[18:19], v[10:11] op_sel_hi:[1,0,1] neg_lo:[0,0,1] neg_hi:[0,0,1]
	v_pk_fma_f32 v[16:17], v[8:9], v[18:19], v[12:13] op_sel_hi:[1,0,1] neg_lo:[0,0,1] neg_hi:[0,0,1]
	v_cvt_pk_bf16_f32 v14, v14, v15
	v_cvt_pk_bf16_f32 v15, v16, v17
	global_store_dwordx2 v22, v[14:15], s[28:29]
	s_cmp_eq_u32 s39, 1
	s_cbranch_scc0 .Lq0_q17
	global_store_dwordx4 v21, v[10:13], s[30:31]
	s_add_u32 s30, s30, 0x2000
	s_addc_u32 s31, s31, 0
.Lq0_q17:
	v_mul_f32_e32 v14, v149, v114
	v_mul_f32_e32 v15, v149, v115
	v_mul_f32_e32 v16, v149, v116
	v_mul_f32_e32 v17, v149, v117
	v_pk_mul_f32 v[14:15], v[2:3], v[14:15]
	v_pk_mul_f32 v[16:17], v[4:5], v[16:17]
	v_pk_add_f32 v[6:7], v[6:7], v[14:15] neg_lo:[0,1] neg_hi:[0,1]
	v_pk_add_f32 v[8:9], v[8:9], v[16:17] neg_lo:[0,1] neg_hi:[0,1]
	s_add_u32 s28, s28, 0x480
	s_addc_u32 s29, s29, 0
	v_mul_f32_e32 v10, v146, v102
	v_mul_f32_e32 v11, v146, v103
	v_mul_f32_e32 v12, v146, v104
	v_mul_f32_e32 v13, v146, v105
	v_pk_mul_f32 v[10:11], v[2:3], v[10:11]
	v_pk_mul_f32 v[12:13], v[4:5], v[12:13]
	v_pk_add_f32 v[6:7], v[6:7], v[10:11]
	v_pk_add_f32 v[8:9], v[8:9], v[12:13]
	v_mov_b32_e32 v18, v27
	v_pk_fma_f32 v[14:15], v[6:7], v[18:19], v[10:11] op_sel_hi:[1,0,1] neg_lo:[0,0,1] neg_hi:[0,0,1]
	v_pk_fma_f32 v[16:17], v[8:9], v[18:19], v[12:13] op_sel_hi:[1,0,1] neg_lo:[0,0,1] neg_hi:[0,0,1]
	v_cvt_pk_bf16_f32 v14, v14, v15
	v_cvt_pk_bf16_f32 v15, v16, v17
	global_store_dwordx2 v22, v[14:15], s[28:29]
	s_cmp_eq_u32 s39, 1
	s_cbranch_scc0 .Lq0_q18
	global_store_dwordx4 v21, v[10:13], s[30:31]
	s_add_u32 s30, s30, 0x2000
	s_addc_u32 s31, s31, 0
.Lq0_q18:
	v_mul_f32_e32 v14, v150, v118
	v_mul_f32_e32 v15, v150, v119
	v_mul_f32_e32 v16, v150, v120
	v_mul_f32_e32 v17, v150, v121
	v_pk_mul_f32 v[14:15], v[2:3], v[14:15]
	v_pk_mul_f32 v[16:17], v[4:5], v[16:17]
	v_pk_add_f32 v[6:7], v[6:7], v[14:15] neg_lo:[0,1] neg_hi:[0,1]
	v_pk_add_f32 v[8:9], v[8:9], v[16:17] neg_lo:[0,1] neg_hi:[0,1]
	s_add_u32 s28, s28, 0x480
	s_addc_u32 s29, s29, 0
	v_mul_f32_e32 v10, v147, v106
	v_mul_f32_e32 v11, v147, v107
	v_mul_f32_e32 v12, v147, v108
	v_mul_f32_e32 v13, v147, v109
	v_pk_mul_f32 v[10:11], v[2:3], v[10:11]
	v_pk_mul_f32 v[12:13], v[4:5], v[12:13]
	v_pk_add_f32 v[6:7], v[6:7], v[10:11]
	v_pk_add_f32 v[8:9], v[8:9], v[12:13]
	v_mov_b32_e32 v18, v27
	v_pk_fma_f32 v[14:15], v[6:7], v[18:19], v[10:11] op_sel_hi:[1,0,1] neg_lo:[0,0,1] neg_hi:[0,0,1]
	v_pk_fma_f32 v[16:17], v[8:9], v[18:19], v[12:13] op_sel_hi:[1,0,1] neg_lo:[0,0,1] neg_hi:[0,0,1]
	v_cvt_pk_bf16_f32 v14, v14, v15
	v_cvt_pk_bf16_f32 v15, v16, v17
	global_store_dwordx2 v22, v[14:15], s[28:29]
	s_cmp_eq_u32 s39, 1
	s_cbranch_scc0 .Lq0_q19
	global_store_dwordx4 v21, v[10:13], s[30:31]
	s_add_u32 s30, s30, 0x2000
	s_addc_u32 s31, s31, 0
.Lq0_q19:
	v_mul_f32_e32 v14, v151, v122
	v_mul_f32_e32 v15, v151, v123
	v_mul_f32_e32 v16, v151, v124
	v_mul_f32_e32 v17, v151, v125
	v_pk_mul_f32 v[14:15], v[2:3], v[14:15]
	v_pk_mul_f32 v[16:17], v[4:5], v[16:17]
	v_pk_add_f32 v[6:7], v[6:7], v[14:15] neg_lo:[0,1] neg_hi:[0,1]
	v_pk_add_f32 v[8:9], v[8:9], v[16:17] neg_lo:[0,1] neg_hi:[0,1]
	s_add_u32 s28, s28, 0x480
	s_addc_u32 s29, s29, 0
	global_load_dwordx4 v[94:97], v21, s[24:25]
	s_add_u32 s24, s24, 0x2000
	s_addc_u32 s25, s25, 0
	global_load_dwordx4 v[98:101], v21, s[24:25]
	s_add_u32 s24, s24, 0x2000
	s_addc_u32 s25, s25, 0
	global_load_dwordx4 v[102:105], v21, s[24:25]
	s_add_u32 s24, s24, 0x2000
	s_addc_u32 s25, s25, 0
	global_load_dwordx4 v[106:109], v21, s[24:25]
	s_add_u32 s24, s24, 0x2000
	s_addc_u32 s25, s25, 0
	global_load_dwordx4 v[110:113], v21, s[26:27]
	s_add_u32 s26, s26, 0x2000
	s_addc_u32 s27, s27, 0
	global_load_dwordx4 v[114:117], v21, s[26:27]
	s_add_u32 s26, s26, 0x2000
	s_addc_u32 s27, s27, 0
	global_load_dwordx4 v[118:121], v21, s[26:27]
	s_add_u32 s26, s26, 0x2000
	s_addc_u32 s27, s27, 0
	global_load_dwordx4 v[122:125], v21, s[26:27]
	s_add_u32 s26, s26, 0x2000
	s_addc_u32 s27, s27, 0
	ds_read_b32 v144, v25 offset:156
	ds_read_b32 v145, v25 offset:160
	ds_read_b32 v146, v25 offset:164
	ds_read_b32 v147, v25 offset:168
	ds_read_b32 v148, v26 offset:96
	ds_read_b32 v149, v26 offset:100
	ds_read_b32 v150, v26 offset:104
	ds_read_b32 v151, v26 offset:108
	s_waitcnt vmcnt(12)
	s_waitcnt lgkmcnt(0)
	v_mul_f32_e32 v10, v66, v34
	v_mul_f32_e32 v11, v66, v35
	v_mul_f32_e32 v12, v66, v36
	v_mul_f32_e32 v13, v66, v37
	v_pk_mul_f32 v[10:11], v[2:3], v[10:11]
	v_pk_mul_f32 v[12:13], v[4:5], v[12:13]
	v_pk_add_f32 v[6:7], v[6:7], v[10:11]
	v_pk_add_f32 v[8:9], v[8:9], v[12:13]
	v_mov_b32_e32 v18, v27
	v_pk_fma_f32 v[14:15], v[6:7], v[18:19], v[10:11] op_sel_hi:[1,0,1] neg_lo:[0,0,1] neg_hi:[0,0,1]
	v_pk_fma_f32 v[16:17], v[8:9], v[18:19], v[12:13] op_sel_hi:[1,0,1] neg_lo:[0,0,1] neg_hi:[0,0,1]
	v_cvt_pk_bf16_f32 v14, v14, v15
	v_cvt_pk_bf16_f32 v15, v16, v17
	global_store_dwordx2 v22, v[14:15], s[28:29]
	s_cmp_eq_u32 s39, 1
	s_cbranch_scc0 .Lq0_q20
	global_store_dwordx4 v21, v[10:13], s[30:31]
	s_add_u32 s30, s30, 0x2000
	s_addc_u32 s31, s31, 0
.Lq0_q20:
	v_mul_f32_e32 v14, v70, v50
	v_mul_f32_e32 v15, v70, v51
	v_mul_f32_e32 v16, v70, v52
	v_mul_f32_e32 v17, v70, v53
	v_pk_mul_f32 v[14:15], v[2:3], v[14:15]
	v_pk_mul_f32 v[16:17], v[4:5], v[16:17]
	v_pk_add_f32 v[6:7], v[6:7], v[14:15] neg_lo:[0,1] neg_hi:[0,1]
	v_pk_add_f32 v[8:9], v[8:9], v[16:17] neg_lo:[0,1] neg_hi:[0,1]
	s_add_u32 s28, s28, 0x480
	s_addc_u32 s29, s29, 0
	v_mul_f32_e32 v10, v67, v38
	v_mul_f32_e32 v11, v67, v39
	v_mul_f32_e32 v12, v67, v40
	v_mul_f32_e32 v13, v67, v41
	v_pk_mul_f32 v[10:11], v[2:3], v[10:11]
	v_pk_mul_f32 v[12:13], v[4:5], v[12:13]
	v_pk_add_f32 v[6:7], v[6:7], v[10:11]
	v_pk_add_f32 v[8:9], v[8:9], v[12:13]
	v_mov_b32_e32 v18, v27
	v_pk_fma_f32 v[14:15], v[6:7], v[18:19], v[10:11] op_sel_hi:[1,0,1] neg_lo:[0,0,1] neg_hi:[0,0,1]
	v_pk_fma_f32 v[16:17], v[8:9], v[18:19], v[12:13] op_sel_hi:[1,0,1] neg_lo:[0,0,1] neg_hi:[0,0,1]
	v_cvt_pk_bf16_f32 v14, v14, v15
	v_cvt_pk_bf16_f32 v15, v16, v17
	global_store_dwordx2 v22, v[14:15], s[28:29]
	s_cmp_eq_u32 s39, 1
	s_cbranch_scc0 .Lq0_q21
	global_store_dwordx4 v21, v[10:13], s[30:31]
	s_add_u32 s30, s30, 0x2000
	s_addc_u32 s31, s31, 0
.Lq0_q21:
	v_mul_f32_e32 v14, v71, v54
	v_mul_f32_e32 v15, v71, v55
	v_mul_f32_e32 v16, v71, v56
	v_mul_f32_e32 v17, v71, v57
	v_pk_mul_f32 v[14:15], v[2:3], v[14:15]
	v_pk_mul_f32 v[16:17], v[4:5], v[16:17]
	v_pk_add_f32 v[6:7], v[6:7], v[14:15] neg_lo:[0,1] neg_hi:[0,1]
	v_pk_add_f32 v[8:9], v[8:9], v[16:17] neg_lo:[0,1] neg_hi:[0,1]
	s_add_u32 s28, s28, 0x480
	s_addc_u32 s29, s29, 0
	v_mul_f32_e32 v10, v68, v42
	v_mul_f32_e32 v11, v68, v43
	v_mul_f32_e32 v12, v68, v44
	v_mul_f32_e32 v13, v68, v45
	v_pk_mul_f32 v[10:11], v[2:3], v[10:11]
	v_pk_mul_f32 v[12:13], v[4:5], v[12:13]
	v_pk_add_f32 v[6:7], v[6:7], v[10:11]
	v_pk_add_f32 v[8:9], v[8:9], v[12:13]
	v_mov_b32_e32 v18, v27
	v_pk_fma_f32 v[14:15], v[6:7], v[18:19], v[10:11] op_sel_hi:[1,0,1] neg_lo:[0,0,1] neg_hi:[0,0,1]
	v_pk_fma_f32 v[16:17], v[8:9], v[18:19], v[12:13] op_sel_hi:[1,0,1] neg_lo:[0,0,1] neg_hi:[0,0,1]
	v_cvt_pk_bf16_f32 v14, v14, v15
	v_cvt_pk_bf16_f32 v15, v16, v17
	global_store_dwordx2 v22, v[14:15], s[28:29]
	s_cmp_eq_u32 s39, 1
	s_cbranch_scc0 .Lq0_q22
	global_store_dwordx4 v21, v[10:13], s[30:31]
	s_add_u32 s30, s30, 0x2000
	s_addc_u32 s31, s31, 0
.Lq0_q22:
	v_mul_f32_e32 v14, v72, v58
	v_mul_f32_e32 v15, v72, v59
	v_mul_f32_e32 v16, v72, v60
	v_mul_f32_e32 v17, v72, v61
	v_pk_mul_f32 v[14:15], v[2:3], v[14:15]
	v_pk_mul_f32 v[16:17], v[4:5], v[16:17]
	v_pk_add_f32 v[6:7], v[6:7], v[14:15] neg_lo:[0,1] neg_hi:[0,1]
	v_pk_add_f32 v[8:9], v[8:9], v[16:17] neg_lo:[0,1] neg_hi:[0,1]
	s_add_u32 s28, s28, 0x480
	s_addc_u32 s29, s29, 0
	v_mul_f32_e32 v10, v69, v46
	v_mul_f32_e32 v11, v69, v47
	v_mul_f32_e32 v12, v69, v48
	v_mul_f32_e32 v13, v69, v49
	v_pk_mul_f32 v[10:11], v[2:3], v[10:11]
	v_pk_mul_f32 v[12:13], v[4:5], v[12:13]
	v_pk_add_f32 v[6:7], v[6:7], v[10:11]
	v_pk_add_f32 v[8:9], v[8:9], v[12:13]
	v_mov_b32_e32 v18, v27
	v_pk_fma_f32 v[14:15], v[6:7], v[18:19], v[10:11] op_sel_hi:[1,0,1] neg_lo:[0,0,1] neg_hi:[0,0,1]
	v_pk_fma_f32 v[16:17], v[8:9], v[18:19], v[12:13] op_sel_hi:[1,0,1] neg_lo:[0,0,1] neg_hi:[0,0,1]
	v_cvt_pk_bf16_f32 v14, v14, v15
	v_cvt_pk_bf16_f32 v15, v16, v17
	global_store_dwordx2 v22, v[14:15], s[28:29]
	s_cmp_eq_u32 s39, 1
	s_cbranch_scc0 .Lq0_q23
	global_store_dwordx4 v21, v[10:13], s[30:31]
	s_add_u32 s30, s30, 0x2000
	s_addc_u32 s31, s31, 0
.Lq0_q23:
	v_mul_f32_e32 v14, v73, v62
	v_mul_f32_e32 v15, v73, v63
	v_mul_f32_e32 v16, v73, v64
	v_mul_f32_e32 v17, v73, v65
	v_pk_mul_f32 v[14:15], v[2:3], v[14:15]
	v_pk_mul_f32 v[16:17], v[4:5], v[16:17]
	v_pk_add_f32 v[6:7], v[6:7], v[14:15] neg_lo:[0,1] neg_hi:[0,1]
	v_pk_add_f32 v[8:9], v[8:9], v[16:17] neg_lo:[0,1] neg_hi:[0,1]
	s_add_u32 s28, s28, 0x480
	s_addc_u32 s29, s29, 0
	global_load_dwordx4 v[34:37], v21, s[24:25]
	s_add_u32 s24, s24, 0x2000
	s_addc_u32 s25, s25, 0
	global_load_dwordx4 v[38:41], v21, s[24:25]
	s_add_u32 s24, s24, 0x2000
	s_addc_u32 s25, s25, 0
	global_load_dwordx4 v[42:45], v21, s[24:25]
	s_add_u32 s24, s24, 0x2000
	s_addc_u32 s25, s25, 0
	global_load_dwordx4 v[46:49], v21, s[24:25]
	s_add_u32 s24, s24, 0x2000
	s_addc_u32 s25, s25, 0
	global_load_dwordx4 v[50:53], v21, s[26:27]
	s_add_u32 s26, s26, 0x2000
	s_addc_u32 s27, s27, 0
	global_load_dwordx4 v[54:57], v21, s[26:27]
	s_add_u32 s26, s26, 0x2000
	s_addc_u32 s27, s27, 0
	global_load_dwordx4 v[58:61], v21, s[26:27]
	s_add_u32 s26, s26, 0x2000
	s_addc_u32 s27, s27, 0
	global_load_dwordx4 v[62:65], v21, s[26:27]
	s_add_u32 s26, s26, 0x2000
	s_addc_u32 s27, s27, 0
	ds_read_b32 v66, v25 offset:172
	ds_read_b32 v67, v25 offset:176
	ds_read_b32 v68, v25 offset:180
	ds_read_b32 v69, v25 offset:184
	ds_read_b32 v70, v26 offset:112
	ds_read_b32 v71, v26 offset:116
	ds_read_b32 v72, v26 offset:120
	ds_read_b32 v73, v26 offset:124
	s_waitcnt vmcnt(12)
	s_waitcnt lgkmcnt(0)
	v_mul_f32_e32 v10, v144, v94
	v_mul_f32_e32 v11, v144, v95
	v_mul_f32_e32 v12, v144, v96
	v_mul_f32_e32 v13, v144, v97
	v_pk_mul_f32 v[10:11], v[2:3], v[10:11]
	v_pk_mul_f32 v[12:13], v[4:5], v[12:13]
	v_pk_add_f32 v[6:7], v[6:7], v[10:11]
	v_pk_add_f32 v[8:9], v[8:9], v[12:13]
	v_mov_b32_e32 v18, v27
	v_pk_fma_f32 v[14:15], v[6:7], v[18:19], v[10:11] op_sel_hi:[1,0,1] neg_lo:[0,0,1] neg_hi:[0,0,1]
	v_pk_fma_f32 v[16:17], v[8:9], v[18:19], v[12:13] op_sel_hi:[1,0,1] neg_lo:[0,0,1] neg_hi:[0,0,1]
	v_cvt_pk_bf16_f32 v14, v14, v15
	v_cvt_pk_bf16_f32 v15, v16, v17
	global_store_dwordx2 v22, v[14:15], s[28:29]
	s_cmp_eq_u32 s39, 1
	s_cbranch_scc0 .Lq0_q24
	global_store_dwordx4 v21, v[10:13], s[30:31]
	s_add_u32 s30, s30, 0x2000
	s_addc_u32 s31, s31, 0
.Lq0_q24:
	v_mul_f32_e32 v14, v148, v110
	v_mul_f32_e32 v15, v148, v111
	v_mul_f32_e32 v16, v148, v112
	v_mul_f32_e32 v17, v148, v113
	v_pk_mul_f32 v[14:15], v[2:3], v[14:15]
	v_pk_mul_f32 v[16:17], v[4:5], v[16:17]
	v_pk_add_f32 v[6:7], v[6:7], v[14:15] neg_lo:[0,1] neg_hi:[0,1]
	v_pk_add_f32 v[8:9], v[8:9], v[16:17] neg_lo:[0,1] neg_hi:[0,1]
	s_add_u32 s28, s28, 0x480
	s_addc_u32 s29, s29, 0
	v_mul_f32_e32 v10, v145, v98
	v_mul_f32_e32 v11, v145, v99
	v_mul_f32_e32 v12, v145, v100
	v_mul_f32_e32 v13, v145, v101
	v_pk_mul_f32 v[10:11], v[2:3], v[10:11]
	v_pk_mul_f32 v[12:13], v[4:5], v[12:13]
	v_pk_add_f32 v[6:7], v[6:7], v[10:11]
	v_pk_add_f32 v[8:9], v[8:9], v[12:13]
	v_mov_b32_e32 v18, v27
	v_pk_fma_f32 v[14:15], v[6:7], v[18:19], v[10:11] op_sel_hi:[1,0,1] neg_lo:[0,0,1] neg_hi:[0,0,1]
	v_pk_fma_f32 v[16:17], v[8:9], v[18:19], v[12:13] op_sel_hi:[1,0,1] neg_lo:[0,0,1] neg_hi:[0,0,1]
	v_cvt_pk_bf16_f32 v14, v14, v15
	v_cvt_pk_bf16_f32 v15, v16, v17
	global_store_dwordx2 v22, v[14:15], s[28:29]
	s_cmp_eq_u32 s39, 1
	s_cbranch_scc0 .Lq0_q25
	global_store_dwordx4 v21, v[10:13], s[30:31]
	s_add_u32 s30, s30, 0x2000
	s_addc_u32 s31, s31, 0

.Lq0_q27:
	v_mul_f32_e32 v14, v151, v122
	v_mul_f32_e32 v15, v151, v123
	v_mul_f32_e32 v16, v151, v124
	v_mul_f32_e32 v17, v151, v125
	v_pk_mul_f32 v[14:15], v[2:3], v[14:15]
	v_pk_mul_f32 v[16:17], v[4:5], v[16:17]
	v_pk_add_f32 v[6:7], v[6:7], v[14:15] neg_lo:[0,1] neg_hi:[0,1]
	v_pk_add_f32 v[8:9], v[8:9], v[16:17] neg_lo:[0,1] neg_hi:[0,1]
	s_add_u32 s28, s28, 0x480
	s_addc_u32 s29, s29, 0
	s_waitcnt vmcnt(4)
	s_waitcnt lgkmcnt(0)
	v_mul_f32_e32 v10, v66, v34
	v_mul_f32_e32 v11, v66, v35
	v_mul_f32_e32 v12, v66, v36
	v_mul_f32_e32 v13, v66, v37
	v_pk_mul_f32 v[10:11], v[2:3], v[10:11]
	v_pk_mul_f32 v[12:13], v[4:5], v[12:13]
	v_pk_add_f32 v[6:7], v[6:7], v[10:11]
	v_pk_add_f32 v[8:9], v[8:9], v[12:13]
	v_mov_b32_e32 v18, v27
	v_pk_fma_f32 v[14:15], v[6:7], v[18:19], v[10:11] op_sel_hi:[1,0,1] neg_lo:[0,0,1] neg_hi:[0,0,1]
	v_pk_fma_f32 v[16:17], v[8:9], v[18:19], v[12:13] op_sel_hi:[1,0,1] neg_lo:[0,0,1] neg_hi:[0,0,1]
	v_cvt_pk_bf16_f32 v14, v14, v15
	v_cvt_pk_bf16_f32 v15, v16, v17
	global_store_dwordx2 v22, v[14:15], s[28:29]
	s_cmp_eq_u32 s39, 1
	s_cbranch_scc0 .Lq0_q28
	global_store_dwordx4 v21, v[10:13], s[30:31]
	s_add_u32 s30, s30, 0x2000
	s_addc_u32 s31, s31, 0

.Lq0_q31:
	v_mul_f32_e32 v14, v73, v62
	v_mul_f32_e32 v15, v73, v63
	v_mul_f32_e32 v16, v73, v64
	v_mul_f32_e32 v17, v73, v65
	v_pk_mul_f32 v[14:15], v[2:3], v[14:15]
	v_pk_mul_f32 v[16:17], v[4:5], v[16:17]
	v_pk_add_f32 v[6:7], v[6:7], v[14:15] neg_lo:[0,1] neg_hi:[0,1]
	v_pk_add_f32 v[8:9], v[8:9], v[16:17] neg_lo:[0,1] neg_hi:[0,1]
	s_add_u32 s28, s28, 0x480
	s_addc_u32 s29, s29, 0
	s_cmp_lt_u32 s76, 32
	s_cbranch_scc0 .Lq0_end
	s_lshl_b32 s50, s76, 3
	s_add_u32 s41, s50, s2
	s_lshl_b32 s12, s41, 13
	s_add_u32 s20, s14, s12
	s_addc_u32 s21, s15, 0
	s_add_u32 s48, s20, 0x1000
	s_addc_u32 s49, s21, 0
	global_load_dwordx4 v[34:37], v23, s[20:21] offset:0
	global_load_dwordx4 v[38:41], v23, s[20:21] offset:1024
	global_load_dwordx4 v[42:45], v23, s[20:21] offset:2048
	global_load_dwordx4 v[46:49], v23, s[20:21] offset:3072
	global_load_dwordx4 v[50:53], v23, s[48:49] offset:0
	global_load_dwordx4 v[54:57], v23, s[48:49] offset:1024
	global_load_dwordx4 v[58:61], v23, s[48:49] offset:2048
	global_load_dwordx4 v[62:65], v23, s[48:49] offset:3072
	s_waitcnt vmcnt(0)
	v_mul_f32_e32 v130, v34, v34
	v_fmac_f32_e32 v130, v35, v35
	v_fmac_f32_e32 v130, v36, v36
	v_fmac_f32_e32 v130, v37, v37
	v_fmac_f32_e32 v130, v38, v38
	v_fmac_f32_e32 v130, v39, v39
	v_fmac_f32_e32 v130, v40, v40
	v_fmac_f32_e32 v130, v41, v41
	v_fmac_f32_e32 v130, v42, v42
	v_fmac_f32_e32 v130, v43, v43
	v_fmac_f32_e32 v130, v44, v44
	v_fmac_f32_e32 v130, v45, v45
	v_fmac_f32_e32 v130, v46, v46
	v_fmac_f32_e32 v130, v47, v47
	v_fmac_f32_e32 v130, v48, v48
	v_fmac_f32_e32 v130, v49, v49
	v_fmac_f32_e32 v130, v50, v50
	v_fmac_f32_e32 v130, v51, v51
	v_fmac_f32_e32 v130, v52, v52
	v_fmac_f32_e32 v130, v53, v53
	v_fmac_f32_e32 v130, v54, v54
	v_fmac_f32_e32 v130, v55, v55
	v_fmac_f32_e32 v130, v56, v56
	v_fmac_f32_e32 v130, v57, v57
	v_fmac_f32_e32 v130, v58, v58
	v_fmac_f32_e32 v130, v59, v59
	v_fmac_f32_e32 v130, v60, v60
	v_fmac_f32_e32 v130, v61, v61
	v_fmac_f32_e32 v130, v62, v62
	v_fmac_f32_e32 v130, v63, v63
	v_fmac_f32_e32 v130, v64, v64
	v_fmac_f32_e32 v130, v65, v65
	v_xor_b32_e32 v136, 4, v20
	ds_bpermute_b32 v133, v136, v130
	s_waitcnt lgkmcnt(0)
	v_add_f32_e32 v130, v130, v133
	v_xor_b32_e32 v136, 8, v20
	ds_bpermute_b32 v133, v136, v130
	s_waitcnt lgkmcnt(0)
	v_add_f32_e32 v130, v130, v133
	v_xor_b32_e32 v136, 16, v20
	ds_bpermute_b32 v133, v136, v130
	s_waitcnt lgkmcnt(0)
	v_add_f32_e32 v130, v130, v133
	v_xor_b32_e32 v136, 32, v20
	ds_bpermute_b32 v133, v136, v130
	s_waitcnt lgkmcnt(0)
	v_add_f32_e32 v130, v130, v133
	v_xor_b32_e32 v136, 64, v20
	ds_bpermute_b32 v133, v136, v130
	s_waitcnt lgkmcnt(0)
	v_add_f32_e32 v130, v130, v133
	v_xor_b32_e32 v136, 128, v20
	ds_bpermute_b32 v133, v136, v130
	s_waitcnt lgkmcnt(0)
	v_add_f32_e32 v130, v130, v133
	s_lshl_b32 s24, s2, 2
	s_add_u32 s24, s24, 0x200
	v_mov_b32_e32 v30, v130
	v_fmamk_f32 v30, v30, 0x3a000000, v171
	v_mul_f32_e32 v28, 0x4f800000, v30
	v_cmp_gt_f32_e32 vcc, s51, v30
	s_nop 1
	v_cndmask_b32_e32 v30, v30, v28, vcc
	v_sqrt_f32_e32 v28, v30
	s_nop 0
	v_add_u32_e32 v29, -1, v28
	v_add_u32_e32 v31, 1, v28
	v_fma_f32 v32, -v29, v28, v30
	v_fma_f32 v33, -v31, v28, v30
	v_cmp_ge_f32_e64 s[34:35], 0, v32
	s_nop 1
	v_cndmask_b32_e64 v28, v28, v29, s[34:35]
	v_cmp_lt_f32_e64 s[34:35], 0, v33
	s_nop 1
	v_cndmask_b32_e64 v28, v28, v31, s[34:35]
	v_mul_f32_e32 v29, 0x37800000, v28
	v_cndmask_b32_e32 v28, v28, v29, vcc
	v_cmp_class_f32_e32 vcc, v30, v172
	s_nop 1
	v_cndmask_b32_e32 v30, v28, v30, vcc
	v_div_scale_f32 v28, s[34:35], v30, v30, 1.0
	v_rcp_f32_e32 v29, v28
	v_div_scale_f32 v31, vcc, 1.0, v30, 1.0
	v_fma_f32 v32, -v28, v29, 1.0
	v_fmac_f32_e32 v29, v32, v29
	v_mul_f32_e32 v32, v31, v29
	v_fma_f32 v33, -v28, v32, v31
	v_fmac_f32_e32 v32, v33, v29
	v_fma_f32 v28, -v28, v32, v31
	v_div_fmas_f32 v28, v28, v29, v32
	v_div_fixup_f32 v30, v28, v30, 1.0
	v_mov_b32_e32 v24, s24
	ds_write_b32 v24, v30
	s_waitcnt lgkmcnt(0)
	s_barrier
	s_mul_i32 s41, s76, 0x1e000
	s_add_u32 s48, s10, s41
	s_addc_u32 s49, s11, 0
	global_load_dwordx4 v[34:37], v21, s[48:49]
	s_add_u32 s48, s48, 0x2000
	s_addc_u32 s49, s49, 0
	global_load_dwordx4 v[38:41], v21, s[48:49]
	s_add_u32 s48, s48, 0x2000
	s_addc_u32 s49, s49, 0
	global_load_dwordx4 v[42:45], v21, s[48:49]
	s_add_u32 s48, s48, 0x2000
	s_addc_u32 s49, s49, 0
	global_load_dwordx4 v[46:49], v21, s[48:49]
	s_add_u32 s48, s48, 0x2000
	s_addc_u32 s49, s49, 0
	global_load_dwordx4 v[50:53], v21, s[48:49]
	s_add_u32 s48, s48, 0x2000
	s_addc_u32 s49, s49, 0
	global_load_dwordx4 v[54:57], v21, s[48:49]
	s_add_u32 s48, s48, 0x2000
	s_addc_u32 s49, s49, 0
	global_load_dwordx4 v[58:61], v21, s[48:49]
	s_add_u32 s48, s48, 0x2000
	s_addc_u32 s49, s49, 0
	global_load_dwordx4 v[62:65], v21, s[48:49]
	s_add_u32 s48, s48, 0x2000
	s_addc_u32 s49, s49, 0
	global_load_dwordx4 v[66:69], v21, s[48:49]
	s_add_u32 s48, s48, 0x2000
	s_addc_u32 s49, s49, 0
	global_load_dwordx4 v[70:73], v21, s[48:49]
	s_add_u32 s48, s48, 0x2000
	s_addc_u32 s49, s49, 0
	global_load_dwordx4 v[74:77], v21, s[48:49]
	s_add_u32 s48, s48, 0x2000
	s_addc_u32 s49, s49, 0
	global_load_dwordx4 v[78:81], v21, s[48:49]
	s_add_u32 s48, s48, 0x2000
	s_addc_u32 s49, s49, 0
	global_load_dwordx4 v[82:85], v21, s[48:49]
	s_add_u32 s48, s48, 0x2000
	s_addc_u32 s49, s49, 0
	global_load_dwordx4 v[86:89], v21, s[48:49]
	s_add_u32 s48, s48, 0x2000
	s_addc_u32 s49, s49, 0
	global_load_dwordx4 v[90:93], v21, s[48:49]
	s_lshl_b32 s12, s50, 13
	s_add_u32 s24, s14, s12
	s_addc_u32 s25, s15, 0
	global_load_dwordx4 v[94:97], v21, s[24:25]
	s_add_u32 s24, s24, 0x2000
	s_addc_u32 s25, s25, 0
	global_load_dwordx4 v[98:101], v21, s[24:25]
	s_add_u32 s24, s24, 0x2000
	s_addc_u32 s25, s25, 0
	global_load_dwordx4 v[102:105], v21, s[24:25]
	s_add_u32 s24, s24, 0x2000
	s_addc_u32 s25, s25, 0
	global_load_dwordx4 v[106:109], v21, s[24:25]
	s_add_u32 s24, s24, 0x2000
	s_addc_u32 s25, s25, 0
	global_load_dwordx4 v[110:113], v21, s[24:25]
	s_add_u32 s24, s24, 0x2000
	s_addc_u32 s25, s25, 0
	global_load_dwordx4 v[114:117], v21, s[24:25]
	s_add_u32 s24, s24, 0x2000
	s_addc_u32 s25, s25, 0
	global_load_dwordx4 v[118:121], v21, s[24:25]
	s_add_u32 s24, s24, 0x2000
	s_addc_u32 s25, s25, 0
	global_load_dwordx4 v[122:125], v21, s[24:25]
	s_add_u32 s12, s50, 0x2000
	s_mul_i32 s12, s12, 0x480
	s_add_u32 s28, s18, s12
	s_addc_u32 s29, s19, 0
	s_add_u32 s41, s41, 0x42f0000
	s_add_u32 s30, s8, s41
	s_addc_u32 s31, s9, 0
	v_mov_b32_e32 v25, 0x200
	ds_read_b32 v162, v25 offset:0
	ds_read_b32 v163, v25 offset:4
	ds_read_b32 v164, v25 offset:8
	ds_read_b32 v165, v25 offset:12
	ds_read_b32 v166, v25 offset:16
	ds_read_b32 v167, v25 offset:20
	ds_read_b32 v32, v25 offset:24
	ds_read_b32 v33, v25 offset:28
	v_mov_b32_e32 v6, 0
	v_mov_b32_e32 v7, 0
	v_mov_b32_e32 v8, 0
	v_mov_b32_e32 v9, 0
	v_mov_b32_e32 v18, v27
	s_waitcnt vmcnt(0)
	s_waitcnt lgkmcnt(0)
	s_cmp_gt_u32 s53, 0
	s_cbranch_scc1 .Lq1_i0
	v_pk_add_f32 v[6:7], v[6:7], v[34:35]
	v_pk_add_f32 v[8:9], v[8:9], v[36:37]
.Lq1_i0:
	s_cmp_gt_u32 s53, 1
	s_cbranch_scc1 .Lq1_i1
	v_pk_add_f32 v[6:7], v[6:7], v[38:39]
	v_pk_add_f32 v[8:9], v[8:9], v[40:41]
.Lq1_i1:
	s_cmp_gt_u32 s53, 2
	s_cbranch_scc1 .Lq1_i2
	v_pk_add_f32 v[6:7], v[6:7], v[42:43]
	v_pk_add_f32 v[8:9], v[8:9], v[44:45]
.Lq1_i2:
	s_cmp_gt_u32 s53, 3
	s_cbranch_scc1 .Lq1_i3
	v_pk_add_f32 v[6:7], v[6:7], v[46:47]
	v_pk_add_f32 v[8:9], v[8:9], v[48:49]
.Lq1_i3:
	s_cmp_gt_u32 s53, 4
	s_cbranch_scc1 .Lq1_i4
	v_pk_add_f32 v[6:7], v[6:7], v[50:51]
	v_pk_add_f32 v[8:9], v[8:9], v[52:53]
.Lq1_i4:
	s_cmp_gt_u32 s53, 5
	s_cbranch_scc1 .Lq1_i5
	v_pk_add_f32 v[6:7], v[6:7], v[54:55]
	v_pk_add_f32 v[8:9], v[8:9], v[56:57]
.Lq1_i5:
	s_cmp_gt_u32 s53, 6
	s_cbranch_scc1 .Lq1_i6
	v_pk_add_f32 v[6:7], v[6:7], v[58:59]
	v_pk_add_f32 v[8:9], v[8:9], v[60:61]
.Lq1_i6:
	s_cmp_gt_u32 s53, 7
	s_cbranch_scc1 .Lq1_i7
	v_pk_add_f32 v[6:7], v[6:7], v[62:63]
	v_pk_add_f32 v[8:9], v[8:9], v[64:65]
.Lq1_i7:
	s_cmp_gt_u32 s53, 8
	s_cbranch_scc1 .Lq1_i8
	v_pk_add_f32 v[6:7], v[6:7], v[66:67]
	v_pk_add_f32 v[8:9], v[8:9], v[68:69]
.Lq1_i8:
	s_cmp_gt_u32 s53, 9
	s_cbranch_scc1 .Lq1_i9
	v_pk_add_f32 v[6:7], v[6:7], v[70:71]
	v_pk_add_f32 v[8:9], v[8:9], v[72:73]
.Lq1_i9:
	s_cmp_gt_u32 s53, 10
	s_cbranch_scc1 .Lq1_i10
	v_pk_add_f32 v[6:7], v[6:7], v[74:75]
	v_pk_add_f32 v[8:9], v[8:9], v[76:77]
.Lq1_i10:
	s_cmp_gt_u32 s53, 11
	s_cbranch_scc1 .Lq1_i11
	v_pk_add_f32 v[6:7], v[6:7], v[78:79]
	v_pk_add_f32 v[8:9], v[8:9], v[80:81]
.Lq1_i11:
	s_cmp_gt_u32 s53, 12
	s_cbranch_scc1 .Lq1_i12
	v_pk_add_f32 v[6:7], v[6:7], v[82:83]
	v_pk_add_f32 v[8:9], v[8:9], v[84:85]
.Lq1_i12:
	s_cmp_gt_u32 s53, 13
	s_cbranch_scc1 .Lq1_i13
	v_pk_add_f32 v[6:7], v[6:7], v[86:87]
	v_pk_add_f32 v[8:9], v[8:9], v[88:89]
.Lq1_i13:
	s_cmp_gt_u32 s53, 14
	s_cbranch_scc1 .Lq1_i14
	v_pk_add_f32 v[6:7], v[6:7], v[90:91]
	v_pk_add_f32 v[8:9], v[8:9], v[92:93]
.Lq1_i14:
	v_mul_f32_e32 v126, v162, v94
	v_mul_f32_e32 v127, v162, v95
	v_mul_f32_e32 v128, v162, v96
	v_mul_f32_e32 v129, v162, v97
	v_pk_mul_f32 v[126:127], v[2:3], v[126:127]
	v_pk_mul_f32 v[128:129], v[4:5], v[128:129]
	v_pk_add_f32 v[6:7], v[6:7], v[126:127]
	v_pk_add_f32 v[8:9], v[8:9], v[128:129]
	v_pk_fma_f32 v[14:15], v[6:7], v[18:19], v[126:127] op_sel_hi:[1,0,1] neg_lo:[0,0,1] neg_hi:[0,0,1]
	v_pk_fma_f32 v[16:17], v[8:9], v[18:19], v[128:129] op_sel_hi:[1,0,1] neg_lo:[0,0,1] neg_hi:[0,0,1]
	v_cvt_pk_bf16_f32 v14, v14, v15
	v_cvt_pk_bf16_f32 v15, v16, v17
	global_store_dwordx2 v22, v[14:15], s[28:29]
	s_add_u32 s28, s28, 0x480
	s_addc_u32 s29, s29, 0
	s_cmp_eq_u32 s1, 16
	s_cbranch_scc0 .Lq1_l0_0
	v_pk_add_f32 v[6:7], v[6:7], v[34:35] neg_lo:[0,1] neg_hi:[0,1]
	v_pk_add_f32 v[8:9], v[8:9], v[36:37] neg_lo:[0,1] neg_hi:[0,1]
	s_branch .Lq1_l0_x

.Lq1_l0_3:
.Lq1_l0_x:
	v_mul_f32_e32 v130, v163, v98
	v_mul_f32_e32 v131, v163, v99
	v_mul_f32_e32 v132, v163, v100
	v_mul_f32_e32 v133, v163, v101
	v_pk_mul_f32 v[130:131], v[2:3], v[130:131]
	v_pk_mul_f32 v[132:133], v[4:5], v[132:133]
	v_pk_add_f32 v[6:7], v[6:7], v[130:131]
	v_pk_add_f32 v[8:9], v[8:9], v[132:133]
	v_pk_fma_f32 v[14:15], v[6:7], v[18:19], v[130:131] op_sel_hi:[1,0,1] neg_lo:[0,0,1] neg_hi:[0,0,1]
	v_pk_fma_f32 v[16:17], v[8:9], v[18:19], v[132:133] op_sel_hi:[1,0,1] neg_lo:[0,0,1] neg_hi:[0,0,1]
	v_cvt_pk_bf16_f32 v14, v14, v15
	v_cvt_pk_bf16_f32 v15, v16, v17
	global_store_dwordx2 v22, v[14:15], s[28:29]
	s_add_u32 s28, s28, 0x480
	s_addc_u32 s29, s29, 0
	s_cmp_eq_u32 s1, 16
	s_cbranch_scc0 .Lq1_l1_0
	v_pk_add_f32 v[6:7], v[6:7], v[38:39] neg_lo:[0,1] neg_hi:[0,1]
	v_pk_add_f32 v[8:9], v[8:9], v[40:41] neg_lo:[0,1] neg_hi:[0,1]
	s_branch .Lq1_l1_x

.Lq1_l1_1:
	s_cmp_eq_u32 s1, 4
	s_cbranch_scc0 .Lq1_l1_2
	v_pk_add_f32 v[6:7], v[6:7], v[86:87] neg_lo:[0,1] neg_hi:[0,1]
	v_pk_add_f32 v[8:9], v[8:9], v[88:89] neg_lo:[0,1] neg_hi:[0,1]
	s_branch .Lq1_l1_x
.Lq1_l1_2:
	s_cmp_eq_u32 s1, 2
	s_cbranch_scc0 .Lq1_l1_3
	v_pk_add_f32 v[6:7], v[6:7], v[126:127] neg_lo:[0,1] neg_hi:[0,1]
	v_pk_add_f32 v[8:9], v[8:9], v[128:129] neg_lo:[0,1] neg_hi:[0,1]
	s_branch .Lq1_l1_x
.Lq1_l1_3:
.Lq1_l1_x:
	v_mul_f32_e32 v134, v164, v102
	v_mul_f32_e32 v135, v164, v103
	v_mul_f32_e32 v136, v164, v104
	v_mul_f32_e32 v137, v164, v105
	v_pk_mul_f32 v[134:135], v[2:3], v[134:135]
	v_pk_mul_f32 v[136:137], v[4:5], v[136:137]
	v_pk_add_f32 v[6:7], v[6:7], v[134:135]
	v_pk_add_f32 v[8:9], v[8:9], v[136:137]
	v_pk_fma_f32 v[14:15], v[6:7], v[18:19], v[134:135] op_sel_hi:[1,0,1] neg_lo:[0,0,1] neg_hi:[0,0,1]
	v_pk_fma_f32 v[16:17], v[8:9], v[18:19], v[136:137] op_sel_hi:[1,0,1] neg_lo:[0,0,1] neg_hi:[0,0,1]
	v_cvt_pk_bf16_f32 v14, v14, v15
	v_cvt_pk_bf16_f32 v15, v16, v17
	global_store_dwordx2 v22, v[14:15], s[28:29]
	s_add_u32 s28, s28, 0x480
	s_addc_u32 s29, s29, 0
	s_cmp_eq_u32 s1, 16
	s_cbranch_scc0 .Lq1_l2_0
	v_pk_add_f32 v[6:7], v[6:7], v[42:43] neg_lo:[0,1] neg_hi:[0,1]
	v_pk_add_f32 v[8:9], v[8:9], v[44:45] neg_lo:[0,1] neg_hi:[0,1]
	s_branch .Lq1_l2_x

.Lq1_l2_1:
	s_cmp_eq_u32 s1, 4
	s_cbranch_scc0 .Lq1_l2_2
	v_pk_add_f32 v[6:7], v[6:7], v[90:91] neg_lo:[0,1] neg_hi:[0,1]
	v_pk_add_f32 v[8:9], v[8:9], v[92:93] neg_lo:[0,1] neg_hi:[0,1]
	s_branch .Lq1_l2_x
.Lq1_l2_2:
	s_cmp_eq_u32 s1, 2
	s_cbranch_scc0 .Lq1_l2_3
	v_pk_add_f32 v[6:7], v[6:7], v[130:131] neg_lo:[0,1] neg_hi:[0,1]
	v_pk_add_f32 v[8:9], v[8:9], v[132:133] neg_lo:[0,1] neg_hi:[0,1]
	s_branch .Lq1_l2_x
.Lq1_l2_3:
.Lq1_l2_x:
	v_mul_f32_e32 v142, v165, v106
	v_mul_f32_e32 v143, v165, v107
	v_mul_f32_e32 v144, v165, v108
	v_mul_f32_e32 v145, v165, v109
	v_pk_mul_f32 v[142:143], v[2:3], v[142:143]
	v_pk_mul_f32 v[144:145], v[4:5], v[144:145]
	v_pk_add_f32 v[6:7], v[6:7], v[142:143]
	v_pk_add_f32 v[8:9], v[8:9], v[144:145]
	v_pk_fma_f32 v[14:15], v[6:7], v[18:19], v[142:143] op_sel_hi:[1,0,1] neg_lo:[0,0,1] neg_hi:[0,0,1]
	v_pk_fma_f32 v[16:17], v[8:9], v[18:19], v[144:145] op_sel_hi:[1,0,1] neg_lo:[0,0,1] neg_hi:[0,0,1]
	v_cvt_pk_bf16_f32 v14, v14, v15
	v_cvt_pk_bf16_f32 v15, v16, v17
	global_store_dwordx2 v22, v[14:15], s[28:29]
	s_add_u32 s28, s28, 0x480
	s_addc_u32 s29, s29, 0
	s_cmp_eq_u32 s1, 16
	s_cbranch_scc0 .Lq1_l3_0
	v_pk_add_f32 v[6:7], v[6:7], v[46:47] neg_lo:[0,1] neg_hi:[0,1]
	v_pk_add_f32 v[8:9], v[8:9], v[48:49] neg_lo:[0,1] neg_hi:[0,1]
	s_branch .Lq1_l3_x
.Lq1_l3_0:
	s_cmp_eq_u32 s1, 8
	s_cbranch_scc0 .Lq1_l3_1
	v_pk_add_f32 v[6:7], v[6:7], v[78:79] neg_lo:[0,1] neg_hi:[0,1]
	v_pk_add_f32 v[8:9], v[8:9], v[80:81] neg_lo:[0,1] neg_hi:[0,1]
	s_branch .Lq1_l3_x
.Lq1_l3_1:
	s_cmp_eq_u32 s1, 4
	s_cbranch_scc0 .Lq1_l3_2
	v_pk_add_f32 v[6:7], v[6:7], v[126:127] neg_lo:[0,1] neg_hi:[0,1]
	v_pk_add_f32 v[8:9], v[8:9], v[128:129] neg_lo:[0,1] neg_hi:[0,1]
	s_branch .Lq1_l3_x

.Lq1_l3_3:
.Lq1_l3_x:
	v_mul_f32_e32 v146, v166, v110
	v_mul_f32_e32 v147, v166, v111
	v_mul_f32_e32 v148, v166, v112
	v_mul_f32_e32 v149, v166, v113
	v_pk_mul_f32 v[146:147], v[2:3], v[146:147]
	v_pk_mul_f32 v[148:149], v[4:5], v[148:149]
	v_pk_add_f32 v[6:7], v[6:7], v[146:147]
	v_pk_add_f32 v[8:9], v[8:9], v[148:149]
	v_pk_fma_f32 v[14:15], v[6:7], v[18:19], v[146:147] op_sel_hi:[1,0,1] neg_lo:[0,0,1] neg_hi:[0,0,1]
	v_pk_fma_f32 v[16:17], v[8:9], v[18:19], v[148:149] op_sel_hi:[1,0,1] neg_lo:[0,0,1] neg_hi:[0,0,1]
	v_cvt_pk_bf16_f32 v14, v14, v15
	v_cvt_pk_bf16_f32 v15, v16, v17
	global_store_dwordx2 v22, v[14:15], s[28:29]
	s_add_u32 s28, s28, 0x480
	s_addc_u32 s29, s29, 0
	s_cmp_eq_u32 s1, 16
	s_cbranch_scc0 .Lq1_l4_0
	v_pk_add_f32 v[6:7], v[6:7], v[50:51] neg_lo:[0,1] neg_hi:[0,1]
	v_pk_add_f32 v[8:9], v[8:9], v[52:53] neg_lo:[0,1] neg_hi:[0,1]
	s_branch .Lq1_l4_x

.Lq1_l4_1:
	s_cmp_eq_u32 s1, 4
	s_cbranch_scc0 .Lq1_l4_2
	v_pk_add_f32 v[6:7], v[6:7], v[130:131] neg_lo:[0,1] neg_hi:[0,1]
	v_pk_add_f32 v[8:9], v[8:9], v[132:133] neg_lo:[0,1] neg_hi:[0,1]
	s_branch .Lq1_l4_x
.Lq1_l4_2:
	s_cmp_eq_u32 s1, 2
	s_cbranch_scc0 .Lq1_l4_3
	v_pk_add_f32 v[6:7], v[6:7], v[142:143] neg_lo:[0,1] neg_hi:[0,1]
	v_pk_add_f32 v[8:9], v[8:9], v[144:145] neg_lo:[0,1] neg_hi:[0,1]
	s_branch .Lq1_l4_x
.Lq1_l4_3:
.Lq1_l4_x:
	v_mul_f32_e32 v150, v167, v114
	v_mul_f32_e32 v151, v167, v115
	v_mul_f32_e32 v152, v167, v116
	v_mul_f32_e32 v153, v167, v117
	v_pk_mul_f32 v[150:151], v[2:3], v[150:151]
	v_pk_mul_f32 v[152:153], v[4:5], v[152:153]
	v_pk_add_f32 v[6:7], v[6:7], v[150:151]
	v_pk_add_f32 v[8:9], v[8:9], v[152:153]
	v_pk_fma_f32 v[14:15], v[6:7], v[18:19], v[150:151] op_sel_hi:[1,0,1] neg_lo:[0,0,1] neg_hi:[0,0,1]
	v_pk_fma_f32 v[16:17], v[8:9], v[18:19], v[152:153] op_sel_hi:[1,0,1] neg_lo:[0,0,1] neg_hi:[0,0,1]
	v_cvt_pk_bf16_f32 v14, v14, v15
	v_cvt_pk_bf16_f32 v15, v16, v17
	global_store_dwordx2 v22, v[14:15], s[28:29]
	s_add_u32 s28, s28, 0x480
	s_addc_u32 s29, s29, 0
	s_cmp_eq_u32 s1, 16
	s_cbranch_scc0 .Lq1_l5_0
	v_pk_add_f32 v[6:7], v[6:7], v[54:55] neg_lo:[0,1] neg_hi:[0,1]
	v_pk_add_f32 v[8:9], v[8:9], v[56:57] neg_lo:[0,1] neg_hi:[0,1]
	s_branch .Lq1_l5_x

.Lq1_l5_1:
	s_cmp_eq_u32 s1, 4
	s_cbranch_scc0 .Lq1_l5_2
	v_pk_add_f32 v[6:7], v[6:7], v[134:135] neg_lo:[0,1] neg_hi:[0,1]
	v_pk_add_f32 v[8:9], v[8:9], v[136:137] neg_lo:[0,1] neg_hi:[0,1]
	s_branch .Lq1_l5_x
.Lq1_l5_2:
	s_cmp_eq_u32 s1, 2
	s_cbranch_scc0 .Lq1_l5_3
	v_pk_add_f32 v[6:7], v[6:7], v[146:147] neg_lo:[0,1] neg_hi:[0,1]
	v_pk_add_f32 v[8:9], v[8:9], v[148:149] neg_lo:[0,1] neg_hi:[0,1]
	s_branch .Lq1_l5_x
.Lq1_l5_3:
.Lq1_l5_x:
	v_mul_f32_e32 v154, v32, v118
	v_mul_f32_e32 v155, v32, v119
	v_mul_f32_e32 v156, v32, v120
	v_mul_f32_e32 v157, v32, v121
	v_pk_mul_f32 v[154:155], v[2:3], v[154:155]
	v_pk_mul_f32 v[156:157], v[4:5], v[156:157]
	v_pk_add_f32 v[6:7], v[6:7], v[154:155]
	v_pk_add_f32 v[8:9], v[8:9], v[156:157]
	v_pk_fma_f32 v[14:15], v[6:7], v[18:19], v[154:155] op_sel_hi:[1,0,1] neg_lo:[0,0,1] neg_hi:[0,0,1]
	v_pk_fma_f32 v[16:17], v[8:9], v[18:19], v[156:157] op_sel_hi:[1,0,1] neg_lo:[0,0,1] neg_hi:[0,0,1]
	v_cvt_pk_bf16_f32 v14, v14, v15
	v_cvt_pk_bf16_f32 v15, v16, v17
	global_store_dwordx2 v22, v[14:15], s[28:29]
	s_add_u32 s28, s28, 0x480
	s_addc_u32 s29, s29, 0
	s_cmp_eq_u32 s1, 16
	s_cbranch_scc0 .Lq1_l6_0
	v_pk_add_f32 v[6:7], v[6:7], v[58:59] neg_lo:[0,1] neg_hi:[0,1]
	v_pk_add_f32 v[8:9], v[8:9], v[60:61] neg_lo:[0,1] neg_hi:[0,1]
	s_branch .Lq1_l6_x

.Lq1_l6_1:
	s_cmp_eq_u32 s1, 4
	s_cbranch_scc0 .Lq1_l6_2
	v_pk_add_f32 v[6:7], v[6:7], v[142:143] neg_lo:[0,1] neg_hi:[0,1]
	v_pk_add_f32 v[8:9], v[8:9], v[144:145] neg_lo:[0,1] neg_hi:[0,1]
	s_branch .Lq1_l6_x
.Lq1_l6_2:
	s_cmp_eq_u32 s1, 2
	s_cbranch_scc0 .Lq1_l6_3
	v_pk_add_f32 v[6:7], v[6:7], v[150:151] neg_lo:[0,1] neg_hi:[0,1]
	v_pk_add_f32 v[8:9], v[8:9], v[152:153] neg_lo:[0,1] neg_hi:[0,1]
	s_branch .Lq1_l6_x
.Lq1_l6_3:
.Lq1_l6_x:
	v_mul_f32_e32 v158, v33, v122
	v_mul_f32_e32 v159, v33, v123
	v_mul_f32_e32 v160, v33, v124
	v_mul_f32_e32 v161, v33, v125
	v_pk_mul_f32 v[158:159], v[2:3], v[158:159]
	v_pk_mul_f32 v[160:161], v[4:5], v[160:161]
	v_pk_add_f32 v[6:7], v[6:7], v[158:159]
	v_pk_add_f32 v[8:9], v[8:9], v[160:161]
	v_pk_fma_f32 v[14:15], v[6:7], v[18:19], v[158:159] op_sel_hi:[1,0,1] neg_lo:[0,0,1] neg_hi:[0,0,1]
	v_pk_fma_f32 v[16:17], v[8:9], v[18:19], v[160:161] op_sel_hi:[1,0,1] neg_lo:[0,0,1] neg_hi:[0,0,1]
	v_cvt_pk_bf16_f32 v14, v14, v15
	v_cvt_pk_bf16_f32 v15, v16, v17
	global_store_dwordx2 v22, v[14:15], s[28:29]
	s_cmp_eq_u32 s1, 16
	s_cbranch_scc0 .Lq1_l7_0
	v_pk_add_f32 v[6:7], v[6:7], v[62:63] neg_lo:[0,1] neg_hi:[0,1]
	v_pk_add_f32 v[8:9], v[8:9], v[64:65] neg_lo:[0,1] neg_hi:[0,1]
	s_branch .Lq1_l7_x
.Lq1_l7_0:
	s_cmp_eq_u32 s1, 8
	s_cbranch_scc0 .Lq1_l7_1
	v_pk_add_f32 v[6:7], v[6:7], v[126:127] neg_lo:[0,1] neg_hi:[0,1]
	v_pk_add_f32 v[8:9], v[8:9], v[128:129] neg_lo:[0,1] neg_hi:[0,1]
	s_branch .Lq1_l7_x
.Lq1_l7_1:
	s_cmp_eq_u32 s1, 4
	s_cbranch_scc0 .Lq1_l7_2
	v_pk_add_f32 v[6:7], v[6:7], v[146:147] neg_lo:[0,1] neg_hi:[0,1]
	v_pk_add_f32 v[8:9], v[8:9], v[148:149] neg_lo:[0,1] neg_hi:[0,1]
	s_branch .Lq1_l7_x
.Lq1_l7_2:
	s_cmp_eq_u32 s1, 2
	s_cbranch_scc0 .Lq1_l7_3
	v_pk_add_f32 v[6:7], v[6:7], v[154:155] neg_lo:[0,1] neg_hi:[0,1]
	v_pk_add_f32 v[8:9], v[8:9], v[156:157] neg_lo:[0,1] neg_hi:[0,1]
	s_branch .Lq1_l7_x
.Lq1_l7_3:
.Lq1_l7_x:
	global_store_dwordx4 v21, v[66:69], s[30:31]
	s_add_u32 s30, s30, 0x2000
	s_addc_u32 s31, s31, 0
	global_store_dwordx4 v21, v[70:73], s[30:31]
	s_add_u32 s30, s30, 0x2000
	s_addc_u32 s31, s31, 0
	global_store_dwordx4 v21, v[74:77], s[30:31]
	s_add_u32 s30, s30, 0x2000
	s_addc_u32 s31, s31, 0
	global_store_dwordx4 v21, v[78:81], s[30:31]
	s_add_u32 s30, s30, 0x2000
	s_addc_u32 s31, s31, 0
	global_store_dwordx4 v21, v[82:85], s[30:31]
	s_add_u32 s30, s30, 0x2000
	s_addc_u32 s31, s31, 0
	global_store_dwordx4 v21, v[86:89], s[30:31]
	s_add_u32 s30, s30, 0x2000
	s_addc_u32 s31, s31, 0
	global_store_dwordx4 v21, v[90:93], s[30:31]
	s_add_u32 s30, s30, 0x2000
	s_addc_u32 s31, s31, 0
	global_store_dwordx4 v21, v[126:129], s[30:31]
	s_add_u32 s30, s30, 0x2000
	s_addc_u32 s31, s31, 0
	global_store_dwordx4 v21, v[130:133], s[30:31]
	s_add_u32 s30, s30, 0x2000
	s_addc_u32 s31, s31, 0
	global_store_dwordx4 v21, v[134:137], s[30:31]
	s_add_u32 s30, s30, 0x2000
	s_addc_u32 s31, s31, 0
	global_store_dwordx4 v21, v[142:145], s[30:31]
	s_add_u32 s30, s30, 0x2000
	s_addc_u32 s31, s31, 0
	global_store_dwordx4 v21, v[146:149], s[30:31]
	s_add_u32 s30, s30, 0x2000
	s_addc_u32 s31, s31, 0
	global_store_dwordx4 v21, v[150:153], s[30:31]
	s_add_u32 s30, s30, 0x2000
	s_addc_u32 s31, s31, 0
	global_store_dwordx4 v21, v[154:157], s[30:31]
	s_add_u32 s30, s30, 0x2000
	s_addc_u32 s31, s31, 0
	global_store_dwordx4 v21, v[158:161], s[30:31]
.Lq0_end:

.LBB0_996:
	s_add_i32 s82, s82, 1
	v_readlane_b32 s18, v254, 18
	s_waitcnt lgkmcnt(0)
	v_readlane_b32 s20, v254, 20
	v_readlane_b32 s22, v254, 22
	v_readlane_b32 s24, v254, 24
	s_cmp_ge_i32 s82, s83
	s_mov_b64 s[0:1], -1
	v_readlane_b32 s19, v254, 19
	v_readlane_b32 s21, v254, 21
	v_readlane_b32 s23, v254, 23
	v_readlane_b32 s25, v254, 25
	s_cbranch_scc1 .LBB0_9
	v_readlane_b32 s0, v253, 4
	v_readlane_b32 s1, v253, 5
	s_andn2_b64 vcc, exec, s[0:1]
	s_cbranch_vccnz .LBB0_1009
	s_waitcnt vmcnt(0)
	s_barrier
	s_mov_b64 s[0:1], exec
	v_readlane_b32 s4, v254, 11
	v_readlane_b32 s5, v254, 12
	s_and_b64 s[4:5], s[0:1], s[4:5]
	s_mov_b64 exec, s[4:5]
	s_cbranch_execz .LBB0_1008
	v_readlane_b32 s4, v253, 0
	v_readlane_b32 s5, v253, 1
	buffer_wbl2 sc1
	s_load_dwordx2 s[4:5], s[4:5], 0x58
	s_mov_b64 s[6:7], exec
	v_mbcnt_lo_u32_b32 v2, s6, 0
	v_mbcnt_hi_u32_b32 v2, s7, v2
	v_cmp_eq_u32_e32 vcc, 0, v2
	s_waitcnt lgkmcnt(0)
	global_load_dword v0, v1, s[4:5] offset:40
	s_and_saveexec_b64 s[8:9], vcc
	s_cbranch_execz .LBB0_1001
	s_bcnt1_i32_b64 s2, s[6:7]
	v_mov_b32_e32 v3, s2
	global_atomic_add v3, v1, v3, s[4:5] offset:32 sc0
